# attention loop (DMA offsets computed at body start) + HGRN pass B packed f32 ops split into scalar ops
# baseline (speedup 1.0000x reference)
.Lat_main:
	s_add_i32 s17, s14, 3
	s_min_u32 s17, s17, s15
	s_mul_i32 s18, s17, 0x30000
	s_lshl_b32 s19, s17, 7
	s_or_b32 s98, s18, 0x80
	s_add_i32 s99, s19, 0x200000
	ds_read_b128 v[224:227], v218 offset:32768
	ds_read_b128 v[228:231], v218 offset:36864
	ds_read_b128 v[232:235], v219 offset:32768
	ds_read_b128 v[236:239], v219 offset:36864
	s_waitcnt lgkmcnt(4)
	v_mfma_f32_32x32x16_bf16 v[80:95], v[144:147], v[140:143], 0
	v_exp_f32_e32 v112, v112
	v_exp_f32_e32 v113, v113
	v_add_f32_e32 v220, v220, v112
	v_cvt_pk_bf16_f32 v240, v112, v113
	v_mfma_f32_32x32x16_bf16 v[64:79], v[148:151], v[140:143], 0
	v_exp_f32_e32 v114, v114
	v_exp_f32_e32 v115, v115
	v_add_f32_e32 v220, v220, v113
	v_cvt_pk_bf16_f32 v241, v114, v115
	v_mfma_f32_32x32x16_bf16 v[80:95], v[152:155], v[136:139], v[80:95]
	v_exp_f32_e32 v116, v116
	v_exp_f32_e32 v117, v117
	v_add_f32_e32 v220, v220, v114
	v_cvt_pk_bf16_f32 v242, v116, v117
	v_mfma_f32_32x32x16_bf16 v[64:79], v[156:159], v[136:139], v[64:79]
	v_exp_f32_e32 v118, v118
	v_exp_f32_e32 v119, v119
	v_add_f32_e32 v220, v220, v115
	v_cvt_pk_bf16_f32 v243, v118, v119
	v_add_u32_e32 v223, v208, v201
	ds_read_b128 v[144:147], v223 offset:16384
	ds_read_b128 v[148:151], v223 offset:20480
	ds_read_b128 v[152:155], v223 offset:24576
	ds_read_b128 v[156:159], v223 offset:28672
	s_waitcnt lgkmcnt(4)
	v_mfma_f32_32x32x16_bf16 v[80:95], v[224:227], v[132:135], v[80:95]
	v_exp_f32_e32 v120, v120
	v_exp_f32_e32 v121, v121
	v_add_f32_e32 v220, v220, v116
	v_cvt_pk_bf16_f32 v244, v120, v121
	v_mfma_f32_32x32x16_bf16 v[64:79], v[228:231], v[132:135], v[64:79]
	v_exp_f32_e32 v122, v122
	v_exp_f32_e32 v123, v123
	v_add_f32_e32 v220, v220, v117
	v_cvt_pk_bf16_f32 v245, v122, v123
	v_mfma_f32_32x32x16_bf16 v[80:95], v[232:235], v[128:131], v[80:95]
	v_exp_f32_e32 v124, v124
	v_exp_f32_e32 v125, v125
	v_add_f32_e32 v220, v220, v118
	v_cvt_pk_bf16_f32 v246, v124, v125
	v_mfma_f32_32x32x16_bf16 v[64:79], v[236:239], v[128:131], v[64:79]
	v_exp_f32_e32 v126, v126
	v_exp_f32_e32 v127, v127
	v_add_f32_e32 v220, v220, v119
	v_cvt_pk_bf16_f32 v247, v126, v127
	v_add_u32_e32 v223, v208, v202
	ds_read_b128 v[224:227], v223 offset:16384
	ds_read_b128 v[228:231], v223 offset:20480
	ds_read_b128 v[232:235], v223 offset:24576
	ds_read_b128 v[236:239], v223 offset:28672
	s_waitcnt lgkmcnt(4)
	v_mfma_f32_32x32x16_bf16 v[48:63], v[144:147], v[240:243], v[48:63]
	v_exp_f32_e32 v96, v96
	v_exp_f32_e32 v97, v97
	v_add_f32_e32 v220, v220, v120
	v_cvt_pk_bf16_f32 v248, v96, v97
	v_mfma_f32_32x32x16_bf16 v[32:47], v[148:151], v[240:243], v[32:47]
	v_exp_f32_e32 v98, v98
	v_exp_f32_e32 v99, v99
	v_add_f32_e32 v220, v220, v121
	v_cvt_pk_bf16_f32 v249, v98, v99
	v_mfma_f32_32x32x16_bf16 v[16:31], v[152:155], v[240:243], v[16:31]
	v_exp_f32_e32 v100, v100
	v_exp_f32_e32 v101, v101
	v_add_f32_e32 v220, v220, v122
	v_cvt_pk_bf16_f32 v250, v100, v101
	v_mfma_f32_32x32x16_bf16 v[0:15], v[156:159], v[240:243], v[0:15]
	v_exp_f32_e32 v102, v102
	v_exp_f32_e32 v103, v103
	v_add_f32_e32 v220, v220, v123
	v_cvt_pk_bf16_f32 v251, v102, v103
	v_add_u32_e32 v223, v208, v203
	ds_read_b128 v[144:147], v223 offset:16384
	ds_read_b128 v[148:151], v223 offset:20480
	ds_read_b128 v[152:155], v223 offset:24576
	ds_read_b128 v[156:159], v223 offset:28672
	s_waitcnt lgkmcnt(4)
	v_mfma_f32_32x32x16_bf16 v[48:63], v[224:227], v[244:247], v[48:63]
	v_exp_f32_e32 v104, v104
	v_exp_f32_e32 v105, v105
	v_add_f32_e32 v220, v220, v104
	v_add_f32_e32 v220, v220, v105
	v_mfma_f32_32x32x16_bf16 v[32:47], v[228:231], v[244:247], v[32:47]
	v_exp_f32_e32 v106, v106
	v_exp_f32_e32 v107, v107
	v_add_f32_e32 v220, v220, v106
	v_add_f32_e32 v220, v220, v107
	v_mfma_f32_32x32x16_bf16 v[16:31], v[232:235], v[244:247], v[16:31]
	v_exp_f32_e32 v108, v108
	v_exp_f32_e32 v109, v109
	v_cvt_pk_bf16_f32 v104, v104, v105
	v_add_f32_e32 v220, v220, v124
	v_mfma_f32_32x32x16_bf16 v[0:15], v[236:239], v[244:247], v[0:15]
	v_exp_f32_e32 v110, v110
	v_exp_f32_e32 v111, v111
	v_cvt_pk_bf16_f32 v105, v106, v107
	v_add_f32_e32 v220, v220, v125
	v_add_u32_e32 v223, v208, v204
	ds_read_b128 v[224:227], v223 offset:16384
	ds_read_b128 v[228:231], v223 offset:20480
	ds_read_b128 v[232:235], v223 offset:24576
	ds_read_b128 v[236:239], v223 offset:28672
	s_waitcnt lgkmcnt(4)
	s_mov_b32 m0, s92
	v_mfma_f32_32x32x16_bf16 v[48:63], v[144:147], v[248:251], v[48:63]
	buffer_load_dwordx4 v205, s[28:31], s18 offen lds
	v_cvt_pk_bf16_f32 v106, v108, v109
	v_cvt_pk_bf16_f32 v107, v110, v111
	s_mov_b32 m0, s93
	v_mfma_f32_32x32x16_bf16 v[32:47], v[148:151], v[248:251], v[32:47]
	buffer_load_dwordx4 v205, s[28:31], s98 offen lds
	v_add_f32_e32 v220, v220, v126
	v_add_f32_e32 v220, v220, v127
	s_mov_b32 m0, s94
	v_mfma_f32_32x32x16_bf16 v[16:31], v[152:155], v[248:251], v[16:31]
	buffer_load_dwordx4 v206, s[36:39], s19 offen lds
	v_add_f32_e32 v220, v220, v96
	v_add_f32_e32 v220, v220, v97
	s_mov_b32 m0, s95
	v_mfma_f32_32x32x16_bf16 v[0:15], v[156:159], v[248:251], v[0:15]
	buffer_load_dwordx4 v206, s[36:39], s99 offen lds
	v_add_f32_e32 v220, v220, v98
	v_add_f32_e32 v220, v220, v99
	s_waitcnt vmcnt(4) lgkmcnt(0)
	s_barrier
	v_add_u32_e32 v223, v209, v201
	v_add_u32_e32 v222, v209, v202
	ds_read_b128 v[144:147], v223
	ds_read_b128 v[148:151], v223 offset:4096
	ds_read_b128 v[152:155], v222
	ds_read_b128 v[156:159], v222 offset:4096
	v_mfma_f32_32x32x16_bf16 v[48:63], v[224:227], v[104:107], v[48:63]
	v_add_f32_e32 v220, v220, v100
	v_add_f32_e32 v220, v220, v101
	v_add_f32_e32 v220, v220, v102
	v_mfma_f32_32x32x16_bf16 v[32:47], v[228:231], v[104:107], v[32:47]
	v_add_f32_e32 v220, v220, v103
	v_add_f32_e32 v220, v220, v108
	v_add_f32_e32 v220, v220, v109
	v_mfma_f32_32x32x16_bf16 v[16:31], v[232:235], v[104:107], v[16:31]
	v_add_f32_e32 v220, v220, v110
	v_add_f32_e32 v220, v220, v111
	v_mfma_f32_32x32x16_bf16 v[0:15], v[236:239], v[104:107], v[0:15]
	s_add_i32 s17, s14, 4
	s_min_u32 s17, s17, s15
	s_mul_i32 s18, s17, 0x30000
	s_lshl_b32 s19, s17, 7
	s_or_b32 s98, s18, 0x80
	s_add_i32 s99, s19, 0x200000
	v_add_u32_e32 v223, v209, v203
	v_add_u32_e32 v222, v209, v204
	ds_read_b128 v[224:227], v223
	ds_read_b128 v[228:231], v223 offset:4096
	ds_read_b128 v[232:235], v222
	ds_read_b128 v[236:239], v222 offset:4096
	s_waitcnt lgkmcnt(4)
	v_mfma_f32_32x32x16_bf16 v[112:127], v[144:147], v[140:143], 0
	v_exp_f32_e32 v80, v80
	v_exp_f32_e32 v81, v81
	v_add_f32_e32 v220, v220, v80
	v_cvt_pk_bf16_f32 v240, v80, v81
	v_mfma_f32_32x32x16_bf16 v[96:111], v[148:151], v[140:143], 0
	v_exp_f32_e32 v82, v82
	v_exp_f32_e32 v83, v83
	v_add_f32_e32 v220, v220, v81
	v_cvt_pk_bf16_f32 v241, v82, v83
	v_mfma_f32_32x32x16_bf16 v[112:127], v[152:155], v[136:139], v[112:127]
	v_exp_f32_e32 v84, v84
	v_exp_f32_e32 v85, v85
	v_add_f32_e32 v220, v220, v82
	v_cvt_pk_bf16_f32 v242, v84, v85
	v_mfma_f32_32x32x16_bf16 v[96:111], v[156:159], v[136:139], v[96:111]
	v_exp_f32_e32 v86, v86
	v_exp_f32_e32 v87, v87
	v_add_f32_e32 v220, v220, v83
	v_cvt_pk_bf16_f32 v243, v86, v87
	v_add_u32_e32 v223, v208, v201
	ds_read_b128 v[144:147], v223 offset:49152
	ds_read_b128 v[148:151], v223 offset:53248
	ds_read_b128 v[152:155], v223 offset:57344
	ds_read_b128 v[156:159], v223 offset:61440
	s_waitcnt lgkmcnt(4)
	v_mfma_f32_32x32x16_bf16 v[112:127], v[224:227], v[132:135], v[112:127]
	v_exp_f32_e32 v88, v88
	v_exp_f32_e32 v89, v89
	v_add_f32_e32 v220, v220, v84
	v_cvt_pk_bf16_f32 v244, v88, v89
	v_mfma_f32_32x32x16_bf16 v[96:111], v[228:231], v[132:135], v[96:111]
	v_exp_f32_e32 v90, v90
	v_exp_f32_e32 v91, v91
	v_add_f32_e32 v220, v220, v85
	v_cvt_pk_bf16_f32 v245, v90, v91
	v_mfma_f32_32x32x16_bf16 v[112:127], v[232:235], v[128:131], v[112:127]
	v_exp_f32_e32 v92, v92
	v_exp_f32_e32 v93, v93
	v_add_f32_e32 v220, v220, v86
	v_cvt_pk_bf16_f32 v246, v92, v93
	v_mfma_f32_32x32x16_bf16 v[96:111], v[236:239], v[128:131], v[96:111]
	v_exp_f32_e32 v94, v94
	v_exp_f32_e32 v95, v95
	v_add_f32_e32 v220, v220, v87
	v_cvt_pk_bf16_f32 v247, v94, v95
	v_add_u32_e32 v223, v208, v202
	ds_read_b128 v[224:227], v223 offset:49152
	ds_read_b128 v[228:231], v223 offset:53248
	ds_read_b128 v[232:235], v223 offset:57344
	ds_read_b128 v[236:239], v223 offset:61440
	s_waitcnt lgkmcnt(4)
	v_mfma_f32_32x32x16_bf16 v[48:63], v[144:147], v[240:243], v[48:63]
	v_exp_f32_e32 v64, v64
	v_exp_f32_e32 v65, v65
	v_add_f32_e32 v220, v220, v88
	v_cvt_pk_bf16_f32 v248, v64, v65
	v_mfma_f32_32x32x16_bf16 v[32:47], v[148:151], v[240:243], v[32:47]
	v_exp_f32_e32 v66, v66
	v_exp_f32_e32 v67, v67
	v_add_f32_e32 v220, v220, v89
	v_cvt_pk_bf16_f32 v249, v66, v67
	v_mfma_f32_32x32x16_bf16 v[16:31], v[152:155], v[240:243], v[16:31]
	v_exp_f32_e32 v68, v68
	v_exp_f32_e32 v69, v69
	v_add_f32_e32 v220, v220, v90
	v_cvt_pk_bf16_f32 v250, v68, v69
	v_mfma_f32_32x32x16_bf16 v[0:15], v[156:159], v[240:243], v[0:15]
	v_exp_f32_e32 v70, v70
	v_exp_f32_e32 v71, v71
	v_add_f32_e32 v220, v220, v91
	v_cvt_pk_bf16_f32 v251, v70, v71
	v_add_u32_e32 v223, v208, v203
	ds_read_b128 v[144:147], v223 offset:49152
	ds_read_b128 v[148:151], v223 offset:53248
	ds_read_b128 v[152:155], v223 offset:57344
	ds_read_b128 v[156:159], v223 offset:61440
	s_waitcnt lgkmcnt(4)
	v_mfma_f32_32x32x16_bf16 v[48:63], v[224:227], v[244:247], v[48:63]
	v_exp_f32_e32 v72, v72
	v_exp_f32_e32 v73, v73
	v_add_f32_e32 v220, v220, v72
	v_add_f32_e32 v220, v220, v73
	v_mfma_f32_32x32x16_bf16 v[32:47], v[228:231], v[244:247], v[32:47]
	v_exp_f32_e32 v74, v74
	v_exp_f32_e32 v75, v75
	v_add_f32_e32 v220, v220, v74
	v_add_f32_e32 v220, v220, v75
	v_mfma_f32_32x32x16_bf16 v[16:31], v[232:235], v[244:247], v[16:31]
	v_exp_f32_e32 v76, v76
	v_exp_f32_e32 v77, v77
	v_cvt_pk_bf16_f32 v72, v72, v73
	v_add_f32_e32 v220, v220, v92
	v_mfma_f32_32x32x16_bf16 v[0:15], v[236:239], v[244:247], v[0:15]
	v_exp_f32_e32 v78, v78
	v_exp_f32_e32 v79, v79
	v_cvt_pk_bf16_f32 v73, v74, v75
	v_add_f32_e32 v220, v220, v93
	v_add_u32_e32 v223, v208, v204
	ds_read_b128 v[224:227], v223 offset:49152
	ds_read_b128 v[228:231], v223 offset:53248
	ds_read_b128 v[232:235], v223 offset:57344
	ds_read_b128 v[236:239], v223 offset:61440
	s_waitcnt lgkmcnt(4)
	s_mov_b32 m0, s72
	v_mfma_f32_32x32x16_bf16 v[48:63], v[144:147], v[248:251], v[48:63]
	buffer_load_dwordx4 v205, s[28:31], s18 offen lds
	v_cvt_pk_bf16_f32 v74, v76, v77
	v_cvt_pk_bf16_f32 v75, v78, v79
	s_mov_b32 m0, s73
	v_mfma_f32_32x32x16_bf16 v[32:47], v[148:151], v[248:251], v[32:47]
	buffer_load_dwordx4 v205, s[28:31], s98 offen lds
	v_add_f32_e32 v220, v220, v94
	v_add_f32_e32 v220, v220, v95
	s_mov_b32 m0, s6
	v_mfma_f32_32x32x16_bf16 v[16:31], v[152:155], v[248:251], v[16:31]
	buffer_load_dwordx4 v206, s[36:39], s19 offen lds
	v_add_f32_e32 v220, v220, v64
	v_add_f32_e32 v220, v220, v65
	s_mov_b32 m0, s7
	v_mfma_f32_32x32x16_bf16 v[0:15], v[156:159], v[248:251], v[0:15]
	buffer_load_dwordx4 v206, s[36:39], s99 offen lds
	v_add_f32_e32 v220, v220, v66
	v_add_f32_e32 v220, v220, v67
	s_waitcnt vmcnt(4) lgkmcnt(0)
	s_barrier
	v_add_u32_e32 v223, v210, v201
	v_add_u32_e32 v222, v210, v202
	ds_read_b128 v[144:147], v223
	ds_read_b128 v[148:151], v223 offset:4096
	ds_read_b128 v[152:155], v222
	ds_read_b128 v[156:159], v222 offset:4096
	v_mfma_f32_32x32x16_bf16 v[48:63], v[224:227], v[72:75], v[48:63]
	v_add_f32_e32 v220, v220, v68
	v_add_f32_e32 v220, v220, v69
	v_add_f32_e32 v220, v220, v70
	v_mfma_f32_32x32x16_bf16 v[32:47], v[228:231], v[72:75], v[32:47]
	v_add_f32_e32 v220, v220, v71
	v_add_f32_e32 v220, v220, v76
	v_add_f32_e32 v220, v220, v77
	v_mfma_f32_32x32x16_bf16 v[16:31], v[232:235], v[72:75], v[16:31]
	v_add_f32_e32 v220, v220, v78
	v_add_f32_e32 v220, v220, v79
	v_mfma_f32_32x32x16_bf16 v[0:15], v[236:239], v[72:75], v[0:15]
	s_add_i32 s17, s14, 5
	s_min_u32 s17, s17, s15
	s_mul_i32 s18, s17, 0x30000
	s_lshl_b32 s19, s17, 7
	s_or_b32 s98, s18, 0x80
	s_add_i32 s99, s19, 0x200000
	v_add_u32_e32 v223, v210, v203
	v_add_u32_e32 v222, v210, v204
	ds_read_b128 v[224:227], v223
	ds_read_b128 v[228:231], v223 offset:4096
	ds_read_b128 v[232:235], v222
	ds_read_b128 v[236:239], v222 offset:4096
	s_waitcnt lgkmcnt(4)
	v_mfma_f32_32x32x16_bf16 v[80:95], v[144:147], v[140:143], 0
	v_exp_f32_e32 v112, v112
	v_exp_f32_e32 v113, v113
	v_add_f32_e32 v220, v220, v112
	v_cvt_pk_bf16_f32 v240, v112, v113
	v_mfma_f32_32x32x16_bf16 v[64:79], v[148:151], v[140:143], 0
	v_exp_f32_e32 v114, v114
	v_exp_f32_e32 v115, v115
	v_add_f32_e32 v220, v220, v113
	v_cvt_pk_bf16_f32 v241, v114, v115
	v_mfma_f32_32x32x16_bf16 v[80:95], v[152:155], v[136:139], v[80:95]
	v_exp_f32_e32 v116, v116
	v_exp_f32_e32 v117, v117
	v_add_f32_e32 v220, v220, v114
	v_cvt_pk_bf16_f32 v242, v116, v117
	v_mfma_f32_32x32x16_bf16 v[64:79], v[156:159], v[136:139], v[64:79]
	v_exp_f32_e32 v118, v118
	v_exp_f32_e32 v119, v119
	v_add_f32_e32 v220, v220, v115
	v_cvt_pk_bf16_f32 v243, v118, v119
	v_add_u32_e32 v223, v211, v201
	ds_read_b128 v[144:147], v223
	ds_read_b128 v[148:151], v223 offset:4096
	ds_read_b128 v[152:155], v223 offset:8192
	ds_read_b128 v[156:159], v223 offset:12288
	s_waitcnt lgkmcnt(4)
	v_mfma_f32_32x32x16_bf16 v[80:95], v[224:227], v[132:135], v[80:95]
	v_exp_f32_e32 v120, v120
	v_exp_f32_e32 v121, v121
	v_add_f32_e32 v220, v220, v116
	v_cvt_pk_bf16_f32 v244, v120, v121
	v_mfma_f32_32x32x16_bf16 v[64:79], v[228:231], v[132:135], v[64:79]
	v_exp_f32_e32 v122, v122
	v_exp_f32_e32 v123, v123
	v_add_f32_e32 v220, v220, v117
	v_cvt_pk_bf16_f32 v245, v122, v123
	v_mfma_f32_32x32x16_bf16 v[80:95], v[232:235], v[128:131], v[80:95]
	v_exp_f32_e32 v124, v124
	v_exp_f32_e32 v125, v125
	v_add_f32_e32 v220, v220, v118
	v_cvt_pk_bf16_f32 v246, v124, v125
	v_mfma_f32_32x32x16_bf16 v[64:79], v[236:239], v[128:131], v[64:79]
	v_exp_f32_e32 v126, v126
	v_exp_f32_e32 v127, v127
	v_add_f32_e32 v220, v220, v119
	v_cvt_pk_bf16_f32 v247, v126, v127
	v_add_u32_e32 v223, v211, v202
	ds_read_b128 v[224:227], v223
	ds_read_b128 v[228:231], v223 offset:4096
	ds_read_b128 v[232:235], v223 offset:8192
	ds_read_b128 v[236:239], v223 offset:12288
	s_waitcnt lgkmcnt(4)
	v_mfma_f32_32x32x16_bf16 v[48:63], v[144:147], v[240:243], v[48:63]
	v_exp_f32_e32 v96, v96
	v_exp_f32_e32 v97, v97
	v_add_f32_e32 v220, v220, v120
	v_cvt_pk_bf16_f32 v248, v96, v97
	v_mfma_f32_32x32x16_bf16 v[32:47], v[148:151], v[240:243], v[32:47]
	v_exp_f32_e32 v98, v98
	v_exp_f32_e32 v99, v99
	v_add_f32_e32 v220, v220, v121
	v_cvt_pk_bf16_f32 v249, v98, v99
	v_mfma_f32_32x32x16_bf16 v[16:31], v[152:155], v[240:243], v[16:31]
	v_exp_f32_e32 v100, v100
	v_exp_f32_e32 v101, v101
	v_add_f32_e32 v220, v220, v122
	v_cvt_pk_bf16_f32 v250, v100, v101
	v_mfma_f32_32x32x16_bf16 v[0:15], v[156:159], v[240:243], v[0:15]
	v_exp_f32_e32 v102, v102
	v_exp_f32_e32 v103, v103
	v_add_f32_e32 v220, v220, v123
	v_cvt_pk_bf16_f32 v251, v102, v103
	v_add_u32_e32 v223, v211, v203
	ds_read_b128 v[144:147], v223
	ds_read_b128 v[148:151], v223 offset:4096
	ds_read_b128 v[152:155], v223 offset:8192
	ds_read_b128 v[156:159], v223 offset:12288
	s_waitcnt lgkmcnt(4)
	v_mfma_f32_32x32x16_bf16 v[48:63], v[224:227], v[244:247], v[48:63]
	v_exp_f32_e32 v104, v104
	v_exp_f32_e32 v105, v105
	v_add_f32_e32 v220, v220, v104
	v_add_f32_e32 v220, v220, v105
	v_mfma_f32_32x32x16_bf16 v[32:47], v[228:231], v[244:247], v[32:47]
	v_exp_f32_e32 v106, v106
	v_exp_f32_e32 v107, v107
	v_add_f32_e32 v220, v220, v106
	v_add_f32_e32 v220, v220, v107
	v_mfma_f32_32x32x16_bf16 v[16:31], v[232:235], v[244:247], v[16:31]
	v_exp_f32_e32 v108, v108
	v_exp_f32_e32 v109, v109
	v_cvt_pk_bf16_f32 v104, v104, v105
	v_add_f32_e32 v220, v220, v124
	v_mfma_f32_32x32x16_bf16 v[0:15], v[236:239], v[244:247], v[0:15]
	v_exp_f32_e32 v110, v110
	v_exp_f32_e32 v111, v111
	v_cvt_pk_bf16_f32 v105, v106, v107
	v_add_f32_e32 v220, v220, v125
	v_add_u32_e32 v223, v211, v204
	ds_read_b128 v[224:227], v223
	ds_read_b128 v[228:231], v223 offset:4096
	ds_read_b128 v[232:235], v223 offset:8192
	ds_read_b128 v[236:239], v223 offset:12288
	s_waitcnt lgkmcnt(4)
	s_mov_b32 m0, s8
	v_mfma_f32_32x32x16_bf16 v[48:63], v[144:147], v[248:251], v[48:63]
	buffer_load_dwordx4 v205, s[28:31], s18 offen lds
	v_cvt_pk_bf16_f32 v106, v108, v109
	v_cvt_pk_bf16_f32 v107, v110, v111
	s_mov_b32 m0, s9
	v_mfma_f32_32x32x16_bf16 v[32:47], v[148:151], v[248:251], v[32:47]
	buffer_load_dwordx4 v205, s[28:31], s98 offen lds
	v_add_f32_e32 v220, v220, v126
	v_add_f32_e32 v220, v220, v127
	s_mov_b32 m0, s58
	v_mfma_f32_32x32x16_bf16 v[16:31], v[152:155], v[248:251], v[16:31]
	buffer_load_dwordx4 v206, s[36:39], s19 offen lds
	v_add_f32_e32 v220, v220, v96
	v_add_f32_e32 v220, v220, v97
	s_mov_b32 m0, s79
	v_mfma_f32_32x32x16_bf16 v[0:15], v[156:159], v[248:251], v[0:15]
	buffer_load_dwordx4 v206, s[36:39], s99 offen lds
	v_add_f32_e32 v220, v220, v98
	v_add_f32_e32 v220, v220, v99
	s_waitcnt vmcnt(4) lgkmcnt(0)
	s_barrier
	ds_read_b128 v[144:147], v175
	ds_read_b128 v[148:151], v175 offset:4096
	ds_read_b128 v[152:155], v217
	ds_read_b128 v[156:159], v217 offset:4096
	v_mfma_f32_32x32x16_bf16 v[48:63], v[224:227], v[104:107], v[48:63]
	v_add_f32_e32 v220, v220, v100
	v_add_f32_e32 v220, v220, v101
	v_add_f32_e32 v220, v220, v102
	v_mfma_f32_32x32x16_bf16 v[32:47], v[228:231], v[104:107], v[32:47]
	v_add_f32_e32 v220, v220, v103
	v_add_f32_e32 v220, v220, v108
	v_add_f32_e32 v220, v220, v109
	v_mfma_f32_32x32x16_bf16 v[16:31], v[232:235], v[104:107], v[16:31]
	v_add_f32_e32 v220, v220, v110
	v_add_f32_e32 v220, v220, v111
	v_mfma_f32_32x32x16_bf16 v[0:15], v[236:239], v[104:107], v[0:15]
	s_add_i32 s17, s14, 6
	s_min_u32 s17, s17, s15
	s_mul_i32 s18, s17, 0x30000
	s_lshl_b32 s19, s17, 7
	s_or_b32 s98, s18, 0x80
	s_add_i32 s99, s19, 0x200000
	ds_read_b128 v[224:227], v218
	ds_read_b128 v[228:231], v218 offset:4096
	ds_read_b128 v[232:235], v219
	ds_read_b128 v[236:239], v219 offset:4096
	s_waitcnt lgkmcnt(4)
	v_mfma_f32_32x32x16_bf16 v[112:127], v[144:147], v[140:143], 0
	v_exp_f32_e32 v80, v80
	v_exp_f32_e32 v81, v81
	v_add_f32_e32 v220, v220, v80
	v_cvt_pk_bf16_f32 v240, v80, v81
	v_mfma_f32_32x32x16_bf16 v[96:111], v[148:151], v[140:143], 0
	v_exp_f32_e32 v82, v82
	v_exp_f32_e32 v83, v83
	v_add_f32_e32 v220, v220, v81
	v_cvt_pk_bf16_f32 v241, v82, v83
	v_mfma_f32_32x32x16_bf16 v[112:127], v[152:155], v[136:139], v[112:127]
	v_exp_f32_e32 v84, v84
	v_exp_f32_e32 v85, v85
	v_add_f32_e32 v220, v220, v82
	v_cvt_pk_bf16_f32 v242, v84, v85
	v_mfma_f32_32x32x16_bf16 v[96:111], v[156:159], v[136:139], v[96:111]
	v_exp_f32_e32 v86, v86
	v_exp_f32_e32 v87, v87
	v_add_f32_e32 v220, v220, v83
	v_cvt_pk_bf16_f32 v243, v86, v87
	v_add_u32_e32 v223, v212, v201
	ds_read_b128 v[144:147], v223
	ds_read_b128 v[148:151], v223 offset:4096
	ds_read_b128 v[152:155], v223 offset:8192
	ds_read_b128 v[156:159], v223 offset:12288
	s_waitcnt lgkmcnt(4)
	v_mfma_f32_32x32x16_bf16 v[112:127], v[224:227], v[132:135], v[112:127]
	v_exp_f32_e32 v88, v88
	v_exp_f32_e32 v89, v89
	v_add_f32_e32 v220, v220, v84
	v_cvt_pk_bf16_f32 v244, v88, v89
	v_mfma_f32_32x32x16_bf16 v[96:111], v[228:231], v[132:135], v[96:111]
	v_exp_f32_e32 v90, v90
	v_exp_f32_e32 v91, v91
	v_add_f32_e32 v220, v220, v85
	v_cvt_pk_bf16_f32 v245, v90, v91
	v_mfma_f32_32x32x16_bf16 v[112:127], v[232:235], v[128:131], v[112:127]
	v_exp_f32_e32 v92, v92
	v_exp_f32_e32 v93, v93
	v_add_f32_e32 v220, v220, v86
	v_cvt_pk_bf16_f32 v246, v92, v93
	v_mfma_f32_32x32x16_bf16 v[96:111], v[236:239], v[128:131], v[96:111]
	v_exp_f32_e32 v94, v94
	v_exp_f32_e32 v95, v95
	v_add_f32_e32 v220, v220, v87
	v_cvt_pk_bf16_f32 v247, v94, v95
	v_add_u32_e32 v223, v212, v202
	ds_read_b128 v[224:227], v223
	ds_read_b128 v[228:231], v223 offset:4096
	ds_read_b128 v[232:235], v223 offset:8192
	ds_read_b128 v[236:239], v223 offset:12288
	s_waitcnt lgkmcnt(4)
	v_mfma_f32_32x32x16_bf16 v[48:63], v[144:147], v[240:243], v[48:63]
	v_exp_f32_e32 v64, v64
	v_exp_f32_e32 v65, v65
	v_add_f32_e32 v220, v220, v88
	v_cvt_pk_bf16_f32 v248, v64, v65
	v_mfma_f32_32x32x16_bf16 v[32:47], v[148:151], v[240:243], v[32:47]
	v_exp_f32_e32 v66, v66
	v_exp_f32_e32 v67, v67
	v_add_f32_e32 v220, v220, v89
	v_cvt_pk_bf16_f32 v249, v66, v67
	v_mfma_f32_32x32x16_bf16 v[16:31], v[152:155], v[240:243], v[16:31]
	v_exp_f32_e32 v68, v68
	v_exp_f32_e32 v69, v69
	v_add_f32_e32 v220, v220, v90
	v_cvt_pk_bf16_f32 v250, v68, v69
	v_mfma_f32_32x32x16_bf16 v[0:15], v[156:159], v[240:243], v[0:15]
	v_exp_f32_e32 v70, v70
	v_exp_f32_e32 v71, v71
	v_add_f32_e32 v220, v220, v91
	v_cvt_pk_bf16_f32 v251, v70, v71
	v_add_u32_e32 v223, v212, v203
	ds_read_b128 v[144:147], v223
	ds_read_b128 v[148:151], v223 offset:4096
	ds_read_b128 v[152:155], v223 offset:8192
	ds_read_b128 v[156:159], v223 offset:12288
	s_waitcnt lgkmcnt(4)
	v_mfma_f32_32x32x16_bf16 v[48:63], v[224:227], v[244:247], v[48:63]
	v_exp_f32_e32 v72, v72
	v_exp_f32_e32 v73, v73
	v_add_f32_e32 v220, v220, v72
	v_add_f32_e32 v220, v220, v73
	v_mfma_f32_32x32x16_bf16 v[32:47], v[228:231], v[244:247], v[32:47]
	v_exp_f32_e32 v74, v74
	v_exp_f32_e32 v75, v75
	v_add_f32_e32 v220, v220, v74
	v_add_f32_e32 v220, v220, v75
	v_mfma_f32_32x32x16_bf16 v[16:31], v[232:235], v[244:247], v[16:31]
	v_exp_f32_e32 v76, v76
	v_exp_f32_e32 v77, v77
	v_cvt_pk_bf16_f32 v72, v72, v73
	v_add_f32_e32 v220, v220, v92
	v_mfma_f32_32x32x16_bf16 v[0:15], v[236:239], v[244:247], v[0:15]
	v_exp_f32_e32 v78, v78
	v_exp_f32_e32 v79, v79
	v_cvt_pk_bf16_f32 v73, v74, v75
	v_add_f32_e32 v220, v220, v93
	v_add_u32_e32 v223, v212, v204
	ds_read_b128 v[224:227], v223
	ds_read_b128 v[228:231], v223 offset:4096
	ds_read_b128 v[232:235], v223 offset:8192
	ds_read_b128 v[236:239], v223 offset:12288
	s_waitcnt lgkmcnt(4)
	s_mov_b32 m0, s52
	v_mfma_f32_32x32x16_bf16 v[48:63], v[144:147], v[248:251], v[48:63]
	buffer_load_dwordx4 v205, s[28:31], s18 offen lds
	v_cvt_pk_bf16_f32 v74, v76, v77
	v_cvt_pk_bf16_f32 v75, v78, v79
	s_mov_b32 m0, s53
	v_mfma_f32_32x32x16_bf16 v[32:47], v[148:151], v[248:251], v[32:47]
	buffer_load_dwordx4 v205, s[28:31], s98 offen lds
	v_add_f32_e32 v220, v220, v94
	v_add_f32_e32 v220, v220, v95
	s_mov_b32 m0, s90
	v_mfma_f32_32x32x16_bf16 v[16:31], v[152:155], v[248:251], v[16:31]
	buffer_load_dwordx4 v206, s[36:39], s19 offen lds
	v_add_f32_e32 v220, v220, v64
	v_add_f32_e32 v220, v220, v65
	s_mov_b32 m0, s91
	v_mfma_f32_32x32x16_bf16 v[0:15], v[156:159], v[248:251], v[0:15]
	buffer_load_dwordx4 v206, s[36:39], s99 offen lds
	v_add_f32_e32 v220, v220, v66
	v_add_f32_e32 v220, v220, v67
	s_waitcnt vmcnt(4) lgkmcnt(0)
	s_barrier
	ds_read_b128 v[144:147], v175 offset:32768
	ds_read_b128 v[148:151], v175 offset:36864
	ds_read_b128 v[152:155], v217 offset:32768
	ds_read_b128 v[156:159], v217 offset:36864
	v_mfma_f32_32x32x16_bf16 v[48:63], v[224:227], v[72:75], v[48:63]
	v_add_f32_e32 v220, v220, v68
	v_add_f32_e32 v220, v220, v69
	v_add_f32_e32 v220, v220, v70
	v_mfma_f32_32x32x16_bf16 v[32:47], v[228:231], v[72:75], v[32:47]
	v_add_f32_e32 v220, v220, v71
	v_add_f32_e32 v220, v220, v76
	v_add_f32_e32 v220, v220, v77
	v_mfma_f32_32x32x16_bf16 v[16:31], v[232:235], v[72:75], v[16:31]
	v_add_f32_e32 v220, v220, v78
	v_add_f32_e32 v220, v220, v79
	v_mfma_f32_32x32x16_bf16 v[0:15], v[236:239], v[72:75], v[0:15]
	s_add_i32 s14, s14, 4
	s_add_i32 s17, s14, 4
	s_cmp_le_u32 s17, s16
	s_cbranch_scc1 .Lat_main
.Lat_rem_check:
	s_cmp_ge_u32 s14, s16
	s_cbranch_scc1 .Lat_exit
	s_add_i32 s17, s14, 3
	s_min_u32 s17, s17, s15
	s_mul_i32 s18, s17, 0x30000
	s_lshl_b32 s19, s17, 7
	s_or_b32 s98, s18, 0x80
	s_add_i32 s99, s19, 0x200000
	ds_read_b128 v[224:227], v218 offset:32768
	ds_read_b128 v[228:231], v218 offset:36864
	ds_read_b128 v[232:235], v219 offset:32768
	ds_read_b128 v[236:239], v219 offset:36864
	s_waitcnt lgkmcnt(4)
	v_mfma_f32_32x32x16_bf16 v[80:95], v[144:147], v[140:143], 0
	v_exp_f32_e32 v112, v112
	v_exp_f32_e32 v113, v113
	v_add_f32_e32 v220, v220, v112
	v_cvt_pk_bf16_f32 v240, v112, v113
	v_mfma_f32_32x32x16_bf16 v[64:79], v[148:151], v[140:143], 0
	v_exp_f32_e32 v114, v114
	v_exp_f32_e32 v115, v115
	v_add_f32_e32 v220, v220, v113
	v_cvt_pk_bf16_f32 v241, v114, v115
	v_mfma_f32_32x32x16_bf16 v[80:95], v[152:155], v[136:139], v[80:95]
	v_exp_f32_e32 v116, v116
	v_exp_f32_e32 v117, v117
	v_add_f32_e32 v220, v220, v114
	v_cvt_pk_bf16_f32 v242, v116, v117
	v_mfma_f32_32x32x16_bf16 v[64:79], v[156:159], v[136:139], v[64:79]
	v_exp_f32_e32 v118, v118
	v_exp_f32_e32 v119, v119
	v_add_f32_e32 v220, v220, v115
	v_cvt_pk_bf16_f32 v243, v118, v119
	v_add_u32_e32 v223, v208, v201
	ds_read_b128 v[144:147], v223 offset:16384
	ds_read_b128 v[148:151], v223 offset:20480
	ds_read_b128 v[152:155], v223 offset:24576
	ds_read_b128 v[156:159], v223 offset:28672
	s_waitcnt lgkmcnt(4)
	v_mfma_f32_32x32x16_bf16 v[80:95], v[224:227], v[132:135], v[80:95]
	v_exp_f32_e32 v120, v120
	v_exp_f32_e32 v121, v121
	v_add_f32_e32 v220, v220, v116
	v_cvt_pk_bf16_f32 v244, v120, v121
	v_mfma_f32_32x32x16_bf16 v[64:79], v[228:231], v[132:135], v[64:79]
	v_exp_f32_e32 v122, v122
	v_exp_f32_e32 v123, v123
	v_add_f32_e32 v220, v220, v117
	v_cvt_pk_bf16_f32 v245, v122, v123
	v_mfma_f32_32x32x16_bf16 v[80:95], v[232:235], v[128:131], v[80:95]
	v_exp_f32_e32 v124, v124
	v_exp_f32_e32 v125, v125
	v_add_f32_e32 v220, v220, v118
	v_cvt_pk_bf16_f32 v246, v124, v125
	v_mfma_f32_32x32x16_bf16 v[64:79], v[236:239], v[128:131], v[64:79]
	v_exp_f32_e32 v126, v126
	v_exp_f32_e32 v127, v127
	v_add_f32_e32 v220, v220, v119
	v_cvt_pk_bf16_f32 v247, v126, v127
	v_add_u32_e32 v223, v208, v202
	ds_read_b128 v[224:227], v223 offset:16384
	ds_read_b128 v[228:231], v223 offset:20480
	ds_read_b128 v[232:235], v223 offset:24576
	ds_read_b128 v[236:239], v223 offset:28672
	s_waitcnt lgkmcnt(4)
	v_mfma_f32_32x32x16_bf16 v[48:63], v[144:147], v[240:243], v[48:63]
	v_exp_f32_e32 v96, v96
	v_exp_f32_e32 v97, v97
	v_add_f32_e32 v220, v220, v120
	v_cvt_pk_bf16_f32 v248, v96, v97
	v_mfma_f32_32x32x16_bf16 v[32:47], v[148:151], v[240:243], v[32:47]
	v_exp_f32_e32 v98, v98
	v_exp_f32_e32 v99, v99
	v_add_f32_e32 v220, v220, v121
	v_cvt_pk_bf16_f32 v249, v98, v99
	v_mfma_f32_32x32x16_bf16 v[16:31], v[152:155], v[240:243], v[16:31]
	v_exp_f32_e32 v100, v100
	v_exp_f32_e32 v101, v101
	v_add_f32_e32 v220, v220, v122
	v_cvt_pk_bf16_f32 v250, v100, v101
	v_mfma_f32_32x32x16_bf16 v[0:15], v[156:159], v[240:243], v[0:15]
	v_exp_f32_e32 v102, v102
	v_exp_f32_e32 v103, v103
	v_add_f32_e32 v220, v220, v123
	v_cvt_pk_bf16_f32 v251, v102, v103
	v_add_u32_e32 v223, v208, v203
	ds_read_b128 v[144:147], v223 offset:16384
	ds_read_b128 v[148:151], v223 offset:20480
	ds_read_b128 v[152:155], v223 offset:24576
	ds_read_b128 v[156:159], v223 offset:28672
	s_waitcnt lgkmcnt(4)
	v_mfma_f32_32x32x16_bf16 v[48:63], v[224:227], v[244:247], v[48:63]
	v_exp_f32_e32 v104, v104
	v_exp_f32_e32 v105, v105
	v_add_f32_e32 v220, v220, v104
	v_add_f32_e32 v220, v220, v105
	v_mfma_f32_32x32x16_bf16 v[32:47], v[228:231], v[244:247], v[32:47]
	v_exp_f32_e32 v106, v106
	v_exp_f32_e32 v107, v107
	v_add_f32_e32 v220, v220, v106
	v_add_f32_e32 v220, v220, v107
	v_mfma_f32_32x32x16_bf16 v[16:31], v[232:235], v[244:247], v[16:31]
	v_exp_f32_e32 v108, v108
	v_exp_f32_e32 v109, v109
	v_cvt_pk_bf16_f32 v104, v104, v105
	v_add_f32_e32 v220, v220, v124
	v_mfma_f32_32x32x16_bf16 v[0:15], v[236:239], v[244:247], v[0:15]
	v_exp_f32_e32 v110, v110
	v_exp_f32_e32 v111, v111
	v_cvt_pk_bf16_f32 v105, v106, v107
	v_add_f32_e32 v220, v220, v125
	v_add_u32_e32 v223, v208, v204
	ds_read_b128 v[224:227], v223 offset:16384
	ds_read_b128 v[228:231], v223 offset:20480
	ds_read_b128 v[232:235], v223 offset:24576
	ds_read_b128 v[236:239], v223 offset:28672
	s_waitcnt lgkmcnt(4)
	s_mov_b32 m0, s92
	v_mfma_f32_32x32x16_bf16 v[48:63], v[144:147], v[248:251], v[48:63]
	buffer_load_dwordx4 v205, s[28:31], s18 offen lds
	v_cvt_pk_bf16_f32 v106, v108, v109
	v_cvt_pk_bf16_f32 v107, v110, v111
	s_mov_b32 m0, s93
	v_mfma_f32_32x32x16_bf16 v[32:47], v[148:151], v[248:251], v[32:47]
	buffer_load_dwordx4 v205, s[28:31], s98 offen lds
	v_add_f32_e32 v220, v220, v126
	v_add_f32_e32 v220, v220, v127
	s_mov_b32 m0, s94
	v_mfma_f32_32x32x16_bf16 v[16:31], v[152:155], v[248:251], v[16:31]
	buffer_load_dwordx4 v206, s[36:39], s19 offen lds
	v_add_f32_e32 v220, v220, v96
	v_add_f32_e32 v220, v220, v97
	s_mov_b32 m0, s95
	v_mfma_f32_32x32x16_bf16 v[0:15], v[156:159], v[248:251], v[0:15]
	buffer_load_dwordx4 v206, s[36:39], s99 offen lds
	v_add_f32_e32 v220, v220, v98
	v_add_f32_e32 v220, v220, v99
	s_waitcnt vmcnt(4) lgkmcnt(0)
	s_barrier
	v_add_u32_e32 v223, v209, v201
	v_add_u32_e32 v222, v209, v202
	ds_read_b128 v[144:147], v223
	ds_read_b128 v[148:151], v223 offset:4096
	ds_read_b128 v[152:155], v222
	ds_read_b128 v[156:159], v222 offset:4096
	v_mfma_f32_32x32x16_bf16 v[48:63], v[224:227], v[104:107], v[48:63]
	v_add_f32_e32 v220, v220, v100
	v_add_f32_e32 v220, v220, v101
	v_add_f32_e32 v220, v220, v102
	v_mfma_f32_32x32x16_bf16 v[32:47], v[228:231], v[104:107], v[32:47]
	v_add_f32_e32 v220, v220, v103
	v_add_f32_e32 v220, v220, v108
	v_add_f32_e32 v220, v220, v109
	v_mfma_f32_32x32x16_bf16 v[16:31], v[232:235], v[104:107], v[16:31]
	v_add_f32_e32 v220, v220, v110
	v_add_f32_e32 v220, v220, v111
	v_mfma_f32_32x32x16_bf16 v[0:15], v[236:239], v[104:107], v[0:15]
	s_add_i32 s17, s14, 4
	s_min_u32 s17, s17, s15
	s_mul_i32 s18, s17, 0x30000
	s_lshl_b32 s19, s17, 7
	s_or_b32 s98, s18, 0x80
	s_add_i32 s99, s19, 0x200000
	v_add_u32_e32 v223, v209, v203
	v_add_u32_e32 v222, v209, v204
	ds_read_b128 v[224:227], v223
	ds_read_b128 v[228:231], v223 offset:4096
	ds_read_b128 v[232:235], v222
	ds_read_b128 v[236:239], v222 offset:4096
	s_waitcnt lgkmcnt(4)
	v_mfma_f32_32x32x16_bf16 v[112:127], v[144:147], v[140:143], 0
	v_exp_f32_e32 v80, v80
	v_exp_f32_e32 v81, v81
	v_add_f32_e32 v220, v220, v80
	v_cvt_pk_bf16_f32 v240, v80, v81
	v_mfma_f32_32x32x16_bf16 v[96:111], v[148:151], v[140:143], 0
	v_exp_f32_e32 v82, v82
	v_exp_f32_e32 v83, v83
	v_add_f32_e32 v220, v220, v81
	v_cvt_pk_bf16_f32 v241, v82, v83
	v_mfma_f32_32x32x16_bf16 v[112:127], v[152:155], v[136:139], v[112:127]
	v_exp_f32_e32 v84, v84
	v_exp_f32_e32 v85, v85
	v_add_f32_e32 v220, v220, v82
	v_cvt_pk_bf16_f32 v242, v84, v85
	v_mfma_f32_32x32x16_bf16 v[96:111], v[156:159], v[136:139], v[96:111]
	v_exp_f32_e32 v86, v86
	v_exp_f32_e32 v87, v87
	v_add_f32_e32 v220, v220, v83
	v_cvt_pk_bf16_f32 v243, v86, v87
	v_add_u32_e32 v223, v208, v201
	ds_read_b128 v[144:147], v223 offset:49152
	ds_read_b128 v[148:151], v223 offset:53248
	ds_read_b128 v[152:155], v223 offset:57344
	ds_read_b128 v[156:159], v223 offset:61440
	s_waitcnt lgkmcnt(4)
	v_mfma_f32_32x32x16_bf16 v[112:127], v[224:227], v[132:135], v[112:127]
	v_exp_f32_e32 v88, v88
	v_exp_f32_e32 v89, v89
	v_add_f32_e32 v220, v220, v84
	v_cvt_pk_bf16_f32 v244, v88, v89
	v_mfma_f32_32x32x16_bf16 v[96:111], v[228:231], v[132:135], v[96:111]
	v_exp_f32_e32 v90, v90
	v_exp_f32_e32 v91, v91
	v_add_f32_e32 v220, v220, v85
	v_cvt_pk_bf16_f32 v245, v90, v91
	v_mfma_f32_32x32x16_bf16 v[112:127], v[232:235], v[128:131], v[112:127]
	v_exp_f32_e32 v92, v92
	v_exp_f32_e32 v93, v93
	v_add_f32_e32 v220, v220, v86
	v_cvt_pk_bf16_f32 v246, v92, v93
	v_mfma_f32_32x32x16_bf16 v[96:111], v[236:239], v[128:131], v[96:111]
	v_exp_f32_e32 v94, v94
	v_exp_f32_e32 v95, v95
	v_add_f32_e32 v220, v220, v87
	v_cvt_pk_bf16_f32 v247, v94, v95
	v_add_u32_e32 v223, v208, v202
	ds_read_b128 v[224:227], v223 offset:49152
	ds_read_b128 v[228:231], v223 offset:53248
	ds_read_b128 v[232:235], v223 offset:57344
	ds_read_b128 v[236:239], v223 offset:61440
	s_waitcnt lgkmcnt(4)
	v_mfma_f32_32x32x16_bf16 v[48:63], v[144:147], v[240:243], v[48:63]
	v_exp_f32_e32 v64, v64
	v_exp_f32_e32 v65, v65
	v_add_f32_e32 v220, v220, v88
	v_cvt_pk_bf16_f32 v248, v64, v65
	v_mfma_f32_32x32x16_bf16 v[32:47], v[148:151], v[240:243], v[32:47]
	v_exp_f32_e32 v66, v66
	v_exp_f32_e32 v67, v67
	v_add_f32_e32 v220, v220, v89
	v_cvt_pk_bf16_f32 v249, v66, v67
	v_mfma_f32_32x32x16_bf16 v[16:31], v[152:155], v[240:243], v[16:31]
	v_exp_f32_e32 v68, v68
	v_exp_f32_e32 v69, v69
	v_add_f32_e32 v220, v220, v90
	v_cvt_pk_bf16_f32 v250, v68, v69
	v_mfma_f32_32x32x16_bf16 v[0:15], v[156:159], v[240:243], v[0:15]
	v_exp_f32_e32 v70, v70
	v_exp_f32_e32 v71, v71
	v_add_f32_e32 v220, v220, v91
	v_cvt_pk_bf16_f32 v251, v70, v71
	v_add_u32_e32 v223, v208, v203
	ds_read_b128 v[144:147], v223 offset:49152
	ds_read_b128 v[148:151], v223 offset:53248
	ds_read_b128 v[152:155], v223 offset:57344
	ds_read_b128 v[156:159], v223 offset:61440
	s_waitcnt lgkmcnt(4)
	v_mfma_f32_32x32x16_bf16 v[48:63], v[224:227], v[244:247], v[48:63]
	v_exp_f32_e32 v72, v72
	v_exp_f32_e32 v73, v73
	v_add_f32_e32 v220, v220, v72
	v_add_f32_e32 v220, v220, v73
	v_mfma_f32_32x32x16_bf16 v[32:47], v[228:231], v[244:247], v[32:47]
	v_exp_f32_e32 v74, v74
	v_exp_f32_e32 v75, v75
	v_add_f32_e32 v220, v220, v74
	v_add_f32_e32 v220, v220, v75
	v_mfma_f32_32x32x16_bf16 v[16:31], v[232:235], v[244:247], v[16:31]
	v_exp_f32_e32 v76, v76
	v_exp_f32_e32 v77, v77
	v_cvt_pk_bf16_f32 v72, v72, v73
	v_add_f32_e32 v220, v220, v92
	v_mfma_f32_32x32x16_bf16 v[0:15], v[236:239], v[244:247], v[0:15]
	v_exp_f32_e32 v78, v78
	v_exp_f32_e32 v79, v79
	v_cvt_pk_bf16_f32 v73, v74, v75
	v_add_f32_e32 v220, v220, v93
	v_add_u32_e32 v223, v208, v204
	ds_read_b128 v[224:227], v223 offset:49152
	ds_read_b128 v[228:231], v223 offset:53248
	ds_read_b128 v[232:235], v223 offset:57344
	ds_read_b128 v[236:239], v223 offset:61440
	s_waitcnt lgkmcnt(4)
	s_mov_b32 m0, s72
	v_mfma_f32_32x32x16_bf16 v[48:63], v[144:147], v[248:251], v[48:63]
	buffer_load_dwordx4 v205, s[28:31], s18 offen lds
	v_cvt_pk_bf16_f32 v74, v76, v77
	v_cvt_pk_bf16_f32 v75, v78, v79
	s_mov_b32 m0, s73
	v_mfma_f32_32x32x16_bf16 v[32:47], v[148:151], v[248:251], v[32:47]
	buffer_load_dwordx4 v205, s[28:31], s98 offen lds
	v_add_f32_e32 v220, v220, v94
	v_add_f32_e32 v220, v220, v95
	s_mov_b32 m0, s6
	v_mfma_f32_32x32x16_bf16 v[16:31], v[152:155], v[248:251], v[16:31]
	buffer_load_dwordx4 v206, s[36:39], s19 offen lds
	v_add_f32_e32 v220, v220, v64
	v_add_f32_e32 v220, v220, v65
	s_mov_b32 m0, s7
	v_mfma_f32_32x32x16_bf16 v[0:15], v[156:159], v[248:251], v[0:15]
	buffer_load_dwordx4 v206, s[36:39], s99 offen lds
	v_add_f32_e32 v220, v220, v66
	v_add_f32_e32 v220, v220, v67
	s_waitcnt vmcnt(4) lgkmcnt(0)
	s_barrier
	v_add_u32_e32 v223, v210, v201
	v_add_u32_e32 v222, v210, v202
	ds_read_b128 v[144:147], v223
	ds_read_b128 v[148:151], v223 offset:4096
	ds_read_b128 v[152:155], v222
	ds_read_b128 v[156:159], v222 offset:4096
	v_mfma_f32_32x32x16_bf16 v[48:63], v[224:227], v[72:75], v[48:63]
	v_add_f32_e32 v220, v220, v68
	v_add_f32_e32 v220, v220, v69
	v_add_f32_e32 v220, v220, v70
	v_mfma_f32_32x32x16_bf16 v[32:47], v[228:231], v[72:75], v[32:47]
	v_add_f32_e32 v220, v220, v71
	v_add_f32_e32 v220, v220, v76
	v_add_f32_e32 v220, v220, v77
	v_mfma_f32_32x32x16_bf16 v[16:31], v[232:235], v[72:75], v[16:31]
	v_add_f32_e32 v220, v220, v78
	v_add_f32_e32 v220, v220, v79
	v_mfma_f32_32x32x16_bf16 v[0:15], v[236:239], v[72:75], v[0:15]
	s_add_i32 s14, s14, 2

.LBB0_427:
	s_lshl_b32 s1, s7, 5
	s_and_b32 s1, s1, 0xffffff80
	v_add_u32_e32 v104, s1, v130
	s_waitcnt lgkmcnt(0)
	v_mov_b64_e32 v[48:49], s[14:15]
	v_mad_i64_i32 v[48:49], s[10:11], v104, s75, v[48:49]
	s_lshl_b32 s40, s6, 2
	v_lshl_add_u64 v[48:49], v[48:49], 0, s[40:41]
	v_lshlrev_b32_e32 v160, 2, v98
	v_lshl_add_u64 v[48:49], v[48:49], 0, v[160:161]
	s_barrier
	ds_read_b128 v[64:67], v132 offset:32768
	ds_read_b128 v[60:63], v132 offset:32784
	ds_read_b128 v[56:59], v132 offset:32800
	ds_read_b128 v[52:55], v132 offset:32816
	global_load_dwordx4 v[84:87], v[48:49], off offset:3072
	global_load_dwordx4 v[88:91], v[48:49], off offset:3088
	global_load_dwordx4 v[92:95], v[48:49], off offset:3104
	s_nop 0
	global_load_dwordx4 v[48:51], v[48:49], off offset:3120
	v_ashrrev_i32_e32 v105, 31, v104
	s_lshl_b32 s40, s6, 1
	v_lshlrev_b32_e32 v160, 1, v98
	s_waitcnt lgkmcnt(0)
	v_mul_f32_e64 v108, v52, v52
	v_mul_f32_e64 v109, v53, v53
	v_mul_f32_e64 v106, v54, v54
	v_mul_f32_e64 v107, v55, v55
	s_mov_b32 s7, s18
	s_waitcnt vmcnt(0)
	v_mul_f32_e32 v68, 0xbfb8aa3b, v48
	v_mul_f32_e32 v111, 0xbfb8aa3b, v49
	v_exp_f32_e32 v110, v68
	v_exp_f32_e32 v111, v111
	global_load_dwordx4 v[68:71], v[100:101], off offset:48
	global_load_dwordx4 v[72:75], v[100:101], off offset:32
	global_load_dwordx4 v[76:79], v[100:101], off offset:16
	global_load_dwordx4 v[80:83], v[100:101], off
	v_add_f32_e64 v110, v110, 1.0
	v_add_f32_e64 v111, v111, 1.0
	s_nop 0
	v_div_scale_f32 v112, s[10:11], v111, v111, 1.0
	v_rcp_f32_e32 v113, v112
	s_nop 0
	v_fma_f32 v114, -v112, v113, 1.0
	v_fmac_f32_e32 v113, v114, v113
	v_div_scale_f32 v114, vcc, 1.0, v111, 1.0
	v_mul_f32_e32 v115, v114, v113
	v_fma_f32 v116, -v112, v115, v114
	v_fmac_f32_e32 v115, v116, v113
	v_fma_f32 v112, -v112, v115, v114
	v_div_fmas_f32 v112, v112, v113, v115
	v_div_fixup_f32 v111, v112, v111, 1.0
	v_div_scale_f32 v112, s[10:11], v110, v110, 1.0
	v_rcp_f32_e32 v113, v112
	s_nop 0
	v_fma_f32 v114, -v112, v113, 1.0
	v_fmac_f32_e32 v113, v114, v113
	v_div_scale_f32 v114, vcc, 1.0, v110, 1.0
	v_mul_f32_e32 v115, v114, v113
	v_fma_f32 v116, -v112, v115, v114
	v_fmac_f32_e32 v115, v116, v113
	v_fma_f32 v112, -v112, v115, v114
	v_div_fmas_f32 v112, v112, v113, v115
	v_div_fixup_f32 v110, v112, v110, 1.0
	v_mul_f32_e32 v112, 0xbfb8aa3b, v94
	v_mul_f32_e32 v113, 0xbfb8aa3b, v95
	v_exp_f32_e32 v112, v112
	v_exp_f32_e32 v113, v113
	v_mul_f32_e64 v48, v48, v110
	v_mul_f32_e64 v49, v49, v111
	v_mul_f32_e64 v110, v58, v58
	v_mul_f32_e64 v111, v59, v59
	v_add_f32_e64 v112, v112, 1.0
	v_add_f32_e64 v113, v113, 1.0
	s_nop 0
	v_div_scale_f32 v114, s[10:11], v113, v113, 1.0
	v_rcp_f32_e32 v115, v114
	s_nop 0
	v_fma_f32 v116, -v114, v115, 1.0
	v_fmac_f32_e32 v115, v116, v115
	v_div_scale_f32 v116, vcc, 1.0, v113, 1.0
	v_mul_f32_e32 v117, v116, v115
	v_fma_f32 v141, -v114, v117, v116
	v_fmac_f32_e32 v117, v141, v115
	v_fma_f32 v114, -v114, v117, v116
	v_div_fmas_f32 v114, v114, v115, v117
	v_div_fixup_f32 v113, v114, v113, 1.0
	v_div_scale_f32 v114, s[10:11], v112, v112, 1.0
	v_rcp_f32_e32 v115, v114
	s_nop 0
	v_fma_f32 v116, -v114, v115, 1.0
	v_fmac_f32_e32 v115, v116, v115
	v_div_scale_f32 v116, vcc, 1.0, v112, 1.0
	v_mul_f32_e32 v117, v116, v115
	v_fma_f32 v141, -v114, v117, v116
	v_fmac_f32_e32 v117, v141, v115
	v_fma_f32 v114, -v114, v117, v116
	v_div_fmas_f32 v114, v114, v115, v117
	v_div_fixup_f32 v112, v114, v112, 1.0
	v_mul_f32_e32 v114, 0xbfb8aa3b, v92
	v_mul_f32_e32 v115, 0xbfb8aa3b, v93
	v_exp_f32_e32 v114, v114
	v_exp_f32_e32 v115, v115
	v_mul_f32_e64 v94, v94, v112
	v_mul_f32_e64 v95, v95, v113
	v_mul_f32_e64 v112, v56, v56
	v_mul_f32_e64 v113, v57, v57
	v_add_f32_e64 v114, v114, 1.0
	v_add_f32_e64 v115, v115, 1.0
	s_nop 0
	v_div_scale_f32 v116, s[10:11], v115, v115, 1.0
	v_rcp_f32_e32 v117, v116
	s_nop 0
	v_fma_f32 v141, -v116, v117, 1.0
	v_fmac_f32_e32 v117, v141, v117
	v_div_scale_f32 v141, vcc, 1.0, v115, 1.0
	v_mul_f32_e32 v142, v141, v117
	v_fma_f32 v143, -v116, v142, v141
	v_fmac_f32_e32 v142, v143, v117
	v_fma_f32 v116, -v116, v142, v141
	v_div_fmas_f32 v116, v116, v117, v142
	v_div_fixup_f32 v115, v116, v115, 1.0
	v_div_scale_f32 v116, s[10:11], v114, v114, 1.0
	v_rcp_f32_e32 v117, v116
	s_nop 0
	v_fma_f32 v141, -v116, v117, 1.0
	v_fmac_f32_e32 v117, v141, v117
	v_div_scale_f32 v141, vcc, 1.0, v114, 1.0
	v_mul_f32_e32 v142, v141, v117
	v_fma_f32 v143, -v116, v142, v141
	v_fmac_f32_e32 v142, v143, v117
	v_fma_f32 v116, -v116, v142, v141
	v_div_fmas_f32 v116, v116, v117, v142
	v_div_fixup_f32 v114, v116, v114, 1.0
	v_mul_f32_e32 v116, 0xbfb8aa3b, v90
	v_mul_f32_e32 v117, 0xbfb8aa3b, v91
	v_exp_f32_e32 v116, v116
	v_exp_f32_e32 v117, v117
	v_mul_f32_e64 v92, v92, v114
	v_mul_f32_e64 v93, v93, v115
	v_mul_f32_e64 v114, v62, v62
	v_mul_f32_e64 v115, v63, v63
	v_add_f32_e64 v116, v116, 1.0
	v_add_f32_e64 v117, v117, 1.0
	s_nop 0
	v_div_scale_f32 v141, s[10:11], v117, v117, 1.0
	v_rcp_f32_e32 v142, v141
	s_nop 0
	v_fma_f32 v143, -v141, v142, 1.0
	v_fmac_f32_e32 v142, v143, v142
	v_div_scale_f32 v143, vcc, 1.0, v117, 1.0
	v_mul_f32_e32 v144, v143, v142
	v_fma_f32 v145, -v141, v144, v143
	v_fmac_f32_e32 v144, v145, v142
	v_fma_f32 v141, -v141, v144, v143
	v_div_fmas_f32 v141, v141, v142, v144
	v_div_fixup_f32 v117, v141, v117, 1.0
	v_div_scale_f32 v141, s[10:11], v116, v116, 1.0
	v_rcp_f32_e32 v142, v141
	s_nop 0
	v_fma_f32 v143, -v141, v142, 1.0
	v_fmac_f32_e32 v142, v143, v142
	v_div_scale_f32 v143, vcc, 1.0, v116, 1.0
	v_mul_f32_e32 v144, v143, v142
	v_fma_f32 v145, -v141, v144, v143
	v_fmac_f32_e32 v144, v145, v142
	v_fma_f32 v141, -v141, v144, v143
	v_div_fmas_f32 v141, v141, v142, v144
	v_div_fixup_f32 v116, v141, v116, 1.0
	v_mul_f32_e32 v141, 0xbfb8aa3b, v88
	v_exp_f32_e32 v142, v141
	v_mul_f32_e32 v141, 0xbfb8aa3b, v89
	v_exp_f32_e32 v143, v141
	v_mul_f32_e64 v90, v90, v116
	v_mul_f32_e64 v91, v91, v117
	v_mul_f32_e64 v116, v60, v60
	v_mul_f32_e64 v117, v61, v61
	v_add_f32_e64 v142, v142, 1.0
	v_add_f32_e64 v143, v143, 1.0
	s_nop 0
	v_div_scale_f32 v141, s[10:11], v143, v143, 1.0
	v_rcp_f32_e32 v144, v141
	s_nop 0
	v_fma_f32 v145, -v141, v144, 1.0
	v_fmac_f32_e32 v144, v145, v144
	v_div_scale_f32 v145, vcc, 1.0, v143, 1.0
	v_mul_f32_e32 v146, v145, v144
	v_fma_f32 v147, -v141, v146, v145
	v_fmac_f32_e32 v146, v147, v144
	v_fma_f32 v141, -v141, v146, v145
	v_div_fmas_f32 v141, v141, v144, v146
	v_div_fixup_f32 v143, v141, v143, 1.0
	v_div_scale_f32 v141, s[10:11], v142, v142, 1.0
	v_rcp_f32_e32 v144, v141
	s_nop 0
	v_fma_f32 v145, -v141, v144, 1.0
	v_fmac_f32_e32 v144, v145, v144
	v_div_scale_f32 v145, vcc, 1.0, v142, 1.0
	v_mul_f32_e32 v146, v145, v144
	v_fma_f32 v147, -v141, v146, v145
	v_fmac_f32_e32 v146, v147, v144
	v_fma_f32 v141, -v141, v146, v145
	v_div_fmas_f32 v141, v141, v144, v146
	v_div_fixup_f32 v142, v141, v142, 1.0
	v_mul_f32_e32 v141, 0xbfb8aa3b, v86
	v_exp_f32_e32 v144, v141
	v_mul_f32_e32 v141, 0xbfb8aa3b, v87
	v_exp_f32_e32 v145, v141
	v_mul_f32_e64 v88, v88, v142
	v_mul_f32_e64 v89, v89, v143
	v_mul_f32_e64 v142, v66, v66
	v_mul_f32_e64 v143, v67, v67
	v_add_f32_e64 v144, v144, 1.0
	v_add_f32_e64 v145, v145, 1.0
	s_nop 0
	v_div_scale_f32 v141, s[10:11], v145, v145, 1.0
	v_rcp_f32_e32 v146, v141
	s_nop 0
	v_fma_f32 v147, -v141, v146, 1.0
	v_fmac_f32_e32 v146, v147, v146
	v_div_scale_f32 v147, vcc, 1.0, v145, 1.0
	v_mul_f32_e32 v148, v147, v146
	v_fma_f32 v149, -v141, v148, v147
	v_fmac_f32_e32 v148, v149, v146
	v_fma_f32 v141, -v141, v148, v147
	v_div_fmas_f32 v141, v141, v146, v148
	v_div_fixup_f32 v145, v141, v145, 1.0
	v_div_scale_f32 v141, s[10:11], v144, v144, 1.0
	v_rcp_f32_e32 v146, v141
	s_nop 0
	v_fma_f32 v147, -v141, v146, 1.0
	v_fmac_f32_e32 v146, v147, v146
	v_div_scale_f32 v147, vcc, 1.0, v144, 1.0
	v_mul_f32_e32 v148, v147, v146
	v_fma_f32 v149, -v141, v148, v147
	v_fmac_f32_e32 v148, v149, v146
	v_fma_f32 v141, -v141, v148, v147
	v_div_fmas_f32 v141, v141, v146, v148
	v_div_fixup_f32 v144, v141, v144, 1.0
	v_mul_f32_e32 v141, 0xbfb8aa3b, v84
	v_exp_f32_e32 v146, v141
	v_mul_f32_e32 v141, 0xbfb8aa3b, v85
	v_exp_f32_e32 v147, v141
	v_mul_f32_e64 v86, v86, v144
	v_mul_f32_e64 v87, v87, v145
	v_mul_f32_e64 v144, v64, v64
	v_mul_f32_e64 v145, v65, v65
	v_add_f32_e64 v146, v146, 1.0
	v_add_f32_e64 v147, v147, 1.0
	s_nop 0
	v_div_scale_f32 v141, s[10:11], v147, v147, 1.0
	v_rcp_f32_e32 v148, v141
	s_nop 0
	v_fma_f32 v149, -v141, v148, 1.0
	v_fmac_f32_e32 v148, v149, v148
	v_div_scale_f32 v149, vcc, 1.0, v147, 1.0
	v_mul_f32_e32 v150, v149, v148
	v_fma_f32 v151, -v141, v150, v149
	v_fmac_f32_e32 v150, v151, v148
	v_fma_f32 v141, -v141, v150, v149
	v_div_fmas_f32 v141, v141, v148, v150
	v_div_fixup_f32 v147, v141, v147, 1.0
	v_div_scale_f32 v141, s[10:11], v146, v146, 1.0
	v_rcp_f32_e32 v148, v141
	s_nop 0
	v_fma_f32 v149, -v141, v148, 1.0
	v_fmac_f32_e32 v148, v149, v148
	v_div_scale_f32 v149, vcc, 1.0, v146, 1.0
	v_mul_f32_e32 v150, v149, v148
	v_fma_f32 v151, -v141, v150, v149
	v_fmac_f32_e32 v150, v151, v148
	v_fma_f32 v141, -v141, v150, v149
	v_div_fmas_f32 v141, v141, v148, v150
	v_div_fixup_f32 v146, v141, v146, 1.0
	v_add_f32_e32 v141, v144, v145
	v_add_f32_e32 v141, v141, v142
	v_add_f32_e32 v141, v141, v143
	v_add_f32_e32 v116, v141, v116
	v_add_f32_e32 v116, v116, v117
	v_add_f32_e32 v114, v116, v114
	v_add_f32_e32 v114, v114, v115
	v_add_f32_e32 v112, v114, v112
	v_add_f32_e32 v112, v112, v113
	v_add_f32_e32 v110, v112, v110
	v_add_f32_e32 v110, v110, v111
	v_add_f32_e32 v108, v110, v108
	v_add_f32_e32 v108, v108, v109
	v_add_f32_e32 v106, v108, v106
	v_add_f32_e32 v106, v106, v107
	v_mul_f32_e64 v84, v84, v146
	v_mul_f32_e64 v85, v85, v147
	s_nop 0
	v_add_f32_dpp v106, v106, v106 quad_perm:[1,0,3,2] row_mask:0xf bank_mask:0xf bound_ctrl:1
	s_nop 1
	v_add_f32_dpp v106, v106, v106 quad_perm:[2,3,0,1] row_mask:0xf bank_mask:0xf bound_ctrl:1
	v_fmamk_f32 v106, v106, 0x3c800000, v182
	v_cmp_gt_f32_e32 vcc, s50, v106
	v_mul_f32_e32 v107, 0x4f800000, v106
	s_nop 0
	v_cndmask_b32_e32 v106, v106, v107, vcc
	v_sqrt_f32_e32 v107, v106
	s_nop 0
	v_add_u32_e32 v108, -1, v107
	v_fma_f32 v109, -v108, v107, v106
	v_cmp_ge_f32_e64 s[10:11], 0, v109
	v_add_u32_e32 v109, 1, v107
	s_nop 0
	v_cndmask_b32_e64 v108, v107, v108, s[10:11]
	v_fma_f32 v107, -v109, v107, v106
	v_cmp_lt_f32_e64 s[10:11], 0, v107
	s_nop 1
	v_cndmask_b32_e64 v107, v108, v109, s[10:11]
	v_mul_f32_e32 v108, 0x37800000, v107
	v_cndmask_b32_e32 v107, v107, v108, vcc
	v_cmp_class_f32_e32 vcc, v106, v183
	s_nop 1
	v_cndmask_b32_e32 v106, v107, v106, vcc
	v_div_scale_f32 v107, s[10:11], v106, v106, 1.0
	v_rcp_f32_e32 v108, v107
	s_nop 0
	v_fma_f32 v109, -v107, v108, 1.0
	v_fmac_f32_e32 v108, v109, v108
	v_div_scale_f32 v109, vcc, 1.0, v106, 1.0
	v_mul_f32_e32 v110, v109, v108
	v_fma_f32 v111, -v107, v110, v109
	v_fmac_f32_e32 v110, v111, v108
	v_fma_f32 v107, -v107, v110, v109
	v_div_fmas_f32 v107, v107, v108, v110
	v_div_fixup_f32 v106, v107, v106, 1.0
	v_mul_f32_e64 v56, v56, v106
	v_mul_f32_e64 v57, v57, v106
	v_mul_f32_e64 v58, v58, v106
	v_mul_f32_e64 v59, v59, v106
	v_mul_f32_e64 v52, v52, v106
	v_mul_f32_e64 v53, v53, v106
	s_waitcnt vmcnt(2)
	v_mul_f32_e64 v56, v56, v72
	v_mul_f32_e64 v57, v57, v73
	v_mul_f32_e64 v58, v58, v74
	v_mul_f32_e64 v59, v59, v75
	v_mul_f32_e64 v52, v52, v68
	v_mul_f32_e64 v53, v53, v69
	v_mul_f32_e64 v56, v56, v92
	v_mul_f32_e64 v57, v57, v93
	v_mul_f32_e64 v58, v58, v94
	v_mul_f32_e64 v59, v59, v95
	v_mul_f32_e64 v48, v52, v48
	v_mul_f32_e64 v49, v53, v49
	v_cvt_pk_bf16_f32 v56, v56, v57
	v_cvt_pk_bf16_f32 v57, v58, v59
	v_cvt_pk_bf16_f32 v58, v48, v49
	v_mul_f32_e32 v48, 0xbfb8aa3b, v50
	v_mul_f32_e32 v49, 0xbfb8aa3b, v51
	v_exp_f32_e32 v48, v48
	v_exp_f32_e32 v49, v49
	v_mul_f32_e64 v52, v54, v106
	v_mul_f32_e64 v53, v55, v106
	v_mul_f32_e64 v64, v64, v106
	v_mul_f32_e64 v65, v65, v106
	v_mul_f32_e64 v66, v66, v106
	v_mul_f32_e64 v67, v67, v106
	v_add_f32_e64 v48, v48, 1.0
	v_add_f32_e64 v49, v49, 1.0
	v_mul_f32_e64 v60, v60, v106
	v_mul_f32_e64 v61, v61, v106
	v_div_scale_f32 v54, s[10:11], v49, v49, 1.0
	v_rcp_f32_e32 v55, v54
	s_waitcnt vmcnt(0)
	v_mul_f32_e64 v64, v80, v64
	v_mul_f32_e64 v65, v81, v65
	v_mul_f32_e64 v66, v66, v82
	v_mul_f32_e64 v67, v67, v83
	v_mul_f32_e64 v60, v60, v76
	v_mul_f32_e64 v61, v61, v77
	v_mul_f32_e64 v64, v84, v64
	v_mul_f32_e64 v65, v85, v65
	v_mul_f32_e64 v66, v66, v86
	v_mul_f32_e64 v67, v67, v87
	v_mul_f32_e64 v60, v60, v88
	v_mul_f32_e64 v61, v61, v89
	v_cvt_pk_bf16_f32 v64, v64, v65
	v_cvt_pk_bf16_f32 v65, v66, v67
	v_cvt_pk_bf16_f32 v66, v60, v61
	v_mul_f32_e64 v60, v62, v106
	v_mul_f32_e64 v61, v63, v106
	v_fma_f32 v59, -v54, v55, 1.0
	v_mul_f32_e64 v60, v60, v78
	v_mul_f32_e64 v61, v61, v79
	v_fmac_f32_e32 v55, v59, v55
	v_mul_f32_e64 v60, v60, v90
	v_mul_f32_e64 v61, v61, v91
	v_div_scale_f32 v59, vcc, 1.0, v49, 1.0
	v_cvt_pk_bf16_f32 v67, v60, v61
	v_mul_f32_e32 v60, v59, v55
	v_fma_f32 v61, -v54, v60, v59
	v_fmac_f32_e32 v60, v61, v55
	v_fma_f32 v54, -v54, v60, v59
	v_div_fmas_f32 v54, v54, v55, v60
	v_div_fixup_f32 v49, v54, v49, 1.0
	v_div_scale_f32 v54, s[10:11], v48, v48, 1.0
	v_rcp_f32_e32 v55, v54
	v_mul_f32_e64 v52, v52, v70
	v_mul_f32_e64 v53, v53, v71
	v_mov_b32_e32 v81, v140
	v_mov_b32_e32 v80, v139
	v_fma_f32 v59, -v54, v55, 1.0
	v_fmac_f32_e32 v55, v59, v55
	v_div_scale_f32 v59, vcc, 1.0, v48, 1.0
	v_mul_f32_e32 v60, v59, v55
	v_fma_f32 v61, -v54, v60, v59
	v_fmac_f32_e32 v60, v61, v55
	v_fma_f32 v54, -v54, v60, v59
	v_div_fmas_f32 v54, v54, v55, v60
	v_div_fixup_f32 v48, v54, v48, 1.0
	v_mul_f32_e64 v48, v50, v48
	v_mul_f32_e64 v49, v51, v49
	s_and_b64 vcc, exec, s[20:21]
	v_mul_f32_e64 v48, v52, v48
	v_mul_f32_e64 v49, v53, v49
	v_mov_b32_e32 v83, v138
	v_cvt_pk_bf16_f32 v59, v48, v49
	v_lshlrev_b64 v[48:49], 11, v[104:105]
	v_lshl_add_u64 v[48:49], s[16:17], 0, v[48:49]
	v_lshl_add_u64 v[48:49], v[48:49], 0, s[40:41]
	v_lshl_add_u64 v[48:49], v[48:49], 0, v[160:161]
	v_mov_b32_e32 v82, v137
	v_mov_b32_e32 v85, v136
	v_mov_b32_e32 v84, v135
	v_mov_b32_e32 v87, v134
	v_mov_b32_e32 v86, v133
	global_store_dwordx4 v[48:49], v[64:67], off
	global_store_dwordx4 v[48:49], v[56:59], off offset:16
	s_barrier
	s_cbranch_vccnz .LBB0_472

.LBB0_433:
	s_waitcnt vmcnt(19)
	v_mul_f32_e32 v54, 0xbfb8aa3b, v0
	v_exp_f32_e32 v54, v54
	v_sub_f32_e32 v53, 1.0, v48
	v_add_f32_e32 v54, 1.0, v54
	v_div_scale_f32 v55, s[18:19], v54, v54, 1.0
	v_rcp_f32_e32 v56, v55
	s_nop 0
	v_fma_f32 v57, -v55, v56, 1.0
	v_fmac_f32_e32 v56, v57, v56
	v_div_scale_f32 v57, vcc, 1.0, v54, 1.0
	v_mul_f32_e32 v58, v57, v56
	v_fma_f32 v59, -v55, v58, v57
	v_fmac_f32_e32 v58, v59, v56
	v_fma_f32 v55, -v55, v58, v57
	v_div_fmas_f32 v55, v55, v56, v58
	v_div_fixup_f32 v54, v55, v54, 1.0
	v_fmac_f32_e32 v48, v54, v53
	v_mul_f32_e32 v54, 0xbfb8aa3b, v1
	v_exp_f32_e32 v54, v54
	v_sub_f32_e32 v53, 1.0, v49
	v_add_f32_e32 v54, 1.0, v54
	v_div_scale_f32 v55, s[18:19], v54, v54, 1.0
	v_rcp_f32_e32 v56, v55
	s_nop 0
	v_fma_f32 v57, -v55, v56, 1.0
	v_fmac_f32_e32 v56, v57, v56
	v_div_scale_f32 v57, vcc, 1.0, v54, 1.0
	v_mul_f32_e32 v58, v57, v56
	v_fma_f32 v59, -v55, v58, v57
	v_fmac_f32_e32 v58, v59, v56
	v_fma_f32 v55, -v55, v58, v57
	v_div_fmas_f32 v55, v55, v56, v58
	v_div_fixup_f32 v54, v55, v54, 1.0
	v_fmac_f32_e32 v49, v54, v53
	v_mul_f32_e32 v54, 0xbfb8aa3b, v2
	v_exp_f32_e32 v54, v54
	v_sub_f32_e32 v53, 1.0, v50
	v_add_f32_e32 v54, 1.0, v54
	v_div_scale_f32 v55, s[18:19], v54, v54, 1.0
	v_rcp_f32_e32 v56, v55
	s_nop 0
	v_fma_f32 v57, -v55, v56, 1.0
	v_fmac_f32_e32 v56, v57, v56
	v_div_scale_f32 v57, vcc, 1.0, v54, 1.0
	v_mul_f32_e32 v58, v57, v56
	v_fma_f32 v59, -v55, v58, v57
	v_fmac_f32_e32 v58, v59, v56
	v_fma_f32 v55, -v55, v58, v57
	v_div_fmas_f32 v55, v55, v56, v58
	v_div_fixup_f32 v54, v55, v54, 1.0
	v_fmac_f32_e32 v50, v54, v53
	v_mul_f32_e32 v54, 0xbfb8aa3b, v3
	v_exp_f32_e32 v54, v54
	v_sub_f32_e32 v53, 1.0, v51
	v_add_f32_e32 v54, 1.0, v54
	v_div_scale_f32 v55, s[18:19], v54, v54, 1.0
	v_rcp_f32_e32 v56, v55
	s_nop 0
	v_fma_f32 v57, -v55, v56, 1.0
	v_fmac_f32_e32 v56, v57, v56
	v_div_scale_f32 v57, vcc, 1.0, v54, 1.0
	v_mul_f32_e32 v58, v57, v56
	v_fma_f32 v59, -v55, v58, v57
	v_fmac_f32_e32 v58, v59, v56
	v_fma_f32 v55, -v55, v58, v57
	v_div_fmas_f32 v55, v55, v56, v58
	v_div_fixup_f32 v54, v55, v54, 1.0
	v_fmac_f32_e32 v51, v54, v53
	ds_write_b128 v125, v[48:51]
	s_waitcnt vmcnt(15)
	ds_write_b128 v125, v[16:19] offset:32768
	v_mul_f32_e32 v48, 0xbfb8aa3b, v8
	v_mul_f32_e32 v49, 0xbfb8aa3b, v9
	v_exp_f32_e32 v48, v48
	v_exp_f32_e32 v49, v49
	v_mul_f32_e32 v50, 0xbfb8aa3b, v10
	v_mul_f32_e32 v51, 0xbfb8aa3b, v11
	v_exp_f32_e32 v50, v50
	v_add_f32_e64 v48, v48, 1.0
	v_add_f32_e64 v49, v49, 1.0
	v_exp_f32_e32 v51, v51
	v_div_scale_f32 v53, s[18:19], v49, v49, 1.0
	v_rcp_f32_e32 v54, v53
	v_add_f32_e64 v50, v50, 1.0
	v_add_f32_e64 v51, v51, 1.0
	v_fma_f32 v55, -v53, v54, 1.0
	v_fmac_f32_e32 v54, v55, v54
	v_div_scale_f32 v55, vcc, 1.0, v49, 1.0
	v_mul_f32_e32 v56, v55, v54
	v_fma_f32 v57, -v53, v56, v55
	v_fmac_f32_e32 v56, v57, v54
	v_fma_f32 v53, -v53, v56, v55
	v_div_fmas_f32 v53, v53, v54, v56
	v_div_fixup_f32 v49, v53, v49, 1.0
	v_div_scale_f32 v53, s[18:19], v48, v48, 1.0
	v_rcp_f32_e32 v54, v53
	s_nop 0
	v_fma_f32 v55, -v53, v54, 1.0
	v_fmac_f32_e32 v54, v55, v54
	v_div_scale_f32 v55, vcc, 1.0, v48, 1.0
	v_mul_f32_e32 v56, v55, v54
	v_fma_f32 v57, -v53, v56, v55
	v_fmac_f32_e32 v56, v57, v54
	v_fma_f32 v53, -v53, v56, v55
	v_div_fmas_f32 v53, v53, v54, v56
	v_div_fixup_f32 v48, v53, v48, 1.0
	v_div_scale_f32 v53, s[18:19], v51, v51, 1.0
	v_rcp_f32_e32 v54, v53
	v_mul_f32_e64 v48, v8, v48
	v_mul_f32_e64 v49, v9, v49
	v_fma_f32 v55, -v53, v54, 1.0
	v_fmac_f32_e32 v54, v55, v54
	v_div_scale_f32 v55, vcc, 1.0, v51, 1.0
	v_mul_f32_e32 v56, v55, v54
	v_fma_f32 v57, -v53, v56, v55
	v_fmac_f32_e32 v56, v57, v54
	v_fma_f32 v53, -v53, v56, v55
	v_div_fmas_f32 v53, v53, v54, v56
	v_div_fixup_f32 v51, v53, v51, 1.0
	v_div_scale_f32 v53, s[18:19], v50, v50, 1.0
	v_rcp_f32_e32 v54, v53
	s_nop 0
	v_fma_f32 v55, -v53, v54, 1.0
	v_fmac_f32_e32 v54, v55, v54
	v_div_scale_f32 v55, vcc, 1.0, v50, 1.0
	v_mul_f32_e32 v56, v55, v54
	v_fma_f32 v57, -v53, v56, v55
	v_fmac_f32_e32 v56, v57, v54
	v_fma_f32 v53, -v53, v56, v55
	v_div_fmas_f32 v53, v53, v54, v56
	v_div_fixup_f32 v50, v53, v50, 1.0
	v_mul_f32_e64 v50, v10, v50
	v_mul_f32_e64 v51, v11, v51
	ds_write_b128 v126, v[48:51]
	v_mov_b32_e32 v49, 0
	s_and_b64 vcc, exec, s[10:11]
	v_mov_b32_e32 v48, 0
	s_cbranch_vccz .LBB0_463
	s_and_b64 vcc, exec, s[10:11]
	s_cbranch_vccz .LBB0_464

.LBB0_438:
	v_mul_f32_e32 v54, 0xbfb8aa3b, v4
	v_exp_f32_e32 v54, v54
	v_sub_f32_e32 v53, 1.0, v48
	v_add_f32_e32 v54, 1.0, v54
	v_div_scale_f32 v55, s[18:19], v54, v54, 1.0
	v_rcp_f32_e32 v56, v55
	s_nop 0
	v_fma_f32 v57, -v55, v56, 1.0
	v_fmac_f32_e32 v56, v57, v56
	v_div_scale_f32 v57, vcc, 1.0, v54, 1.0
	v_mul_f32_e32 v58, v57, v56
	v_fma_f32 v59, -v55, v58, v57
	v_fmac_f32_e32 v58, v59, v56
	v_fma_f32 v55, -v55, v58, v57
	v_div_fmas_f32 v55, v55, v56, v58
	v_div_fixup_f32 v54, v55, v54, 1.0
	v_fmac_f32_e32 v48, v54, v53
	v_mul_f32_e32 v54, 0xbfb8aa3b, v5
	v_exp_f32_e32 v54, v54
	v_sub_f32_e32 v53, 1.0, v49
	v_add_f32_e32 v54, 1.0, v54
	v_div_scale_f32 v55, s[18:19], v54, v54, 1.0
	v_rcp_f32_e32 v56, v55
	s_nop 0
	v_fma_f32 v57, -v55, v56, 1.0
	v_fmac_f32_e32 v56, v57, v56
	v_div_scale_f32 v57, vcc, 1.0, v54, 1.0
	v_mul_f32_e32 v58, v57, v56
	v_fma_f32 v59, -v55, v58, v57
	v_fmac_f32_e32 v58, v59, v56
	v_fma_f32 v55, -v55, v58, v57
	v_div_fmas_f32 v55, v55, v56, v58
	v_div_fixup_f32 v54, v55, v54, 1.0
	v_fmac_f32_e32 v49, v54, v53
	v_mul_f32_e32 v54, 0xbfb8aa3b, v6
	v_exp_f32_e32 v54, v54
	v_sub_f32_e32 v53, 1.0, v50
	v_add_f32_e32 v54, 1.0, v54
	v_div_scale_f32 v55, s[18:19], v54, v54, 1.0
	v_rcp_f32_e32 v56, v55
	s_nop 0
	v_fma_f32 v57, -v55, v56, 1.0
	v_fmac_f32_e32 v56, v57, v56
	v_div_scale_f32 v57, vcc, 1.0, v54, 1.0
	v_mul_f32_e32 v58, v57, v56
	v_fma_f32 v59, -v55, v58, v57
	v_fmac_f32_e32 v58, v59, v56
	v_fma_f32 v55, -v55, v58, v57
	v_div_fmas_f32 v55, v55, v56, v58
	v_div_fixup_f32 v54, v55, v54, 1.0
	v_fmac_f32_e32 v50, v54, v53
	v_mul_f32_e32 v54, 0xbfb8aa3b, v7
	v_exp_f32_e32 v54, v54
	v_sub_f32_e32 v53, 1.0, v51
	v_add_f32_e32 v54, 1.0, v54
	v_div_scale_f32 v55, s[18:19], v54, v54, 1.0
	v_rcp_f32_e32 v56, v55
	s_nop 0
	v_fma_f32 v57, -v55, v56, 1.0
	v_fmac_f32_e32 v56, v57, v56
	v_div_scale_f32 v57, vcc, 1.0, v54, 1.0
	v_mul_f32_e32 v58, v57, v56
	v_fma_f32 v59, -v55, v58, v57
	v_fmac_f32_e32 v58, v59, v56
	v_fma_f32 v55, -v55, v58, v57
	v_div_fmas_f32 v55, v55, v56, v58
	v_div_fixup_f32 v54, v55, v54, 1.0
	v_fmac_f32_e32 v51, v54, v53
	ds_write_b128 v125, v[48:51] offset:8192
	ds_write_b128 v125, v[12:15] offset:40960
	s_waitcnt vmcnt(14)
	v_mul_f32_e32 v48, 0xbfb8aa3b, v24
	v_mul_f32_e32 v49, 0xbfb8aa3b, v25
	v_exp_f32_e32 v48, v48
	v_exp_f32_e32 v49, v49
	v_mul_f32_e32 v50, 0xbfb8aa3b, v26
	v_mul_f32_e32 v51, 0xbfb8aa3b, v27
	v_exp_f32_e32 v50, v50
	v_add_f32_e64 v48, v48, 1.0
	v_add_f32_e64 v49, v49, 1.0
	v_exp_f32_e32 v51, v51
	v_div_scale_f32 v53, s[18:19], v49, v49, 1.0
	v_rcp_f32_e32 v54, v53
	v_add_f32_e64 v50, v50, 1.0
	v_add_f32_e64 v51, v51, 1.0
	v_fma_f32 v55, -v53, v54, 1.0
	v_fmac_f32_e32 v54, v55, v54
	v_div_scale_f32 v55, vcc, 1.0, v49, 1.0
	v_mul_f32_e32 v56, v55, v54
	v_fma_f32 v57, -v53, v56, v55
	v_fmac_f32_e32 v56, v57, v54
	v_fma_f32 v53, -v53, v56, v55
	v_div_fmas_f32 v53, v53, v54, v56
	v_div_fixup_f32 v49, v53, v49, 1.0
	v_div_scale_f32 v53, s[18:19], v48, v48, 1.0
	v_rcp_f32_e32 v54, v53
	s_nop 0
	v_fma_f32 v55, -v53, v54, 1.0
	v_fmac_f32_e32 v54, v55, v54
	v_div_scale_f32 v55, vcc, 1.0, v48, 1.0
	v_mul_f32_e32 v56, v55, v54
	v_fma_f32 v57, -v53, v56, v55
	v_fmac_f32_e32 v56, v57, v54
	v_fma_f32 v53, -v53, v56, v55
	v_div_fmas_f32 v53, v53, v54, v56
	v_div_fixup_f32 v48, v53, v48, 1.0
	v_div_scale_f32 v53, s[18:19], v51, v51, 1.0
	v_rcp_f32_e32 v54, v53
	v_mul_f32_e64 v48, v24, v48
	v_mul_f32_e64 v49, v25, v49
	v_fma_f32 v55, -v53, v54, 1.0
	v_fmac_f32_e32 v54, v55, v54
	v_div_scale_f32 v55, vcc, 1.0, v51, 1.0
	v_mul_f32_e32 v56, v55, v54
	v_fma_f32 v57, -v53, v56, v55
	v_fmac_f32_e32 v56, v57, v54
	v_fma_f32 v53, -v53, v56, v55
	v_div_fmas_f32 v53, v53, v54, v56
	v_div_fixup_f32 v51, v53, v51, 1.0
	v_div_scale_f32 v53, s[18:19], v50, v50, 1.0
	v_rcp_f32_e32 v54, v53
	s_nop 0
	v_fma_f32 v55, -v53, v54, 1.0
	v_fmac_f32_e32 v54, v55, v54
	v_div_scale_f32 v55, vcc, 1.0, v50, 1.0
	v_mul_f32_e32 v56, v55, v54
	v_fma_f32 v57, -v53, v56, v55
	v_fmac_f32_e32 v56, v57, v54
	v_fma_f32 v53, -v53, v56, v55
	v_div_fmas_f32 v53, v53, v54, v56
	v_div_fixup_f32 v50, v53, v50, 1.0
	v_mul_f32_e64 v50, v26, v50
	v_mul_f32_e64 v51, v27, v51
	ds_write_b128 v127, v[48:51]
	v_mov_b32_e32 v49, 0
	s_and_b64 vcc, exec, s[10:11]
	v_mov_b32_e32 v48, 0
	s_cbranch_vccz .LBB0_466
	s_and_b64 vcc, exec, s[10:11]
	s_cbranch_vccz .LBB0_467

.LBB0_443:
	s_waitcnt vmcnt(13)
	v_mul_f32_e32 v54, 0xbfb8aa3b, v20
	v_exp_f32_e32 v54, v54
	v_sub_f32_e32 v53, 1.0, v48
	v_add_f32_e32 v54, 1.0, v54
	v_div_scale_f32 v55, s[18:19], v54, v54, 1.0
	v_rcp_f32_e32 v56, v55
	s_nop 0
	v_fma_f32 v57, -v55, v56, 1.0
	v_fmac_f32_e32 v56, v57, v56
	v_div_scale_f32 v57, vcc, 1.0, v54, 1.0
	v_mul_f32_e32 v58, v57, v56
	v_fma_f32 v59, -v55, v58, v57
	v_fmac_f32_e32 v58, v59, v56
	v_fma_f32 v55, -v55, v58, v57
	v_div_fmas_f32 v55, v55, v56, v58
	v_div_fixup_f32 v54, v55, v54, 1.0
	v_fmac_f32_e32 v48, v54, v53
	v_mul_f32_e32 v54, 0xbfb8aa3b, v21
	v_exp_f32_e32 v54, v54
	v_sub_f32_e32 v53, 1.0, v49
	v_add_f32_e32 v54, 1.0, v54
	v_div_scale_f32 v55, s[18:19], v54, v54, 1.0
	v_rcp_f32_e32 v56, v55
	s_nop 0
	v_fma_f32 v57, -v55, v56, 1.0
	v_fmac_f32_e32 v56, v57, v56
	v_div_scale_f32 v57, vcc, 1.0, v54, 1.0
	v_mul_f32_e32 v58, v57, v56
	v_fma_f32 v59, -v55, v58, v57
	v_fmac_f32_e32 v58, v59, v56
	v_fma_f32 v55, -v55, v58, v57
	v_div_fmas_f32 v55, v55, v56, v58
	v_div_fixup_f32 v54, v55, v54, 1.0
	v_fmac_f32_e32 v49, v54, v53
	v_mul_f32_e32 v54, 0xbfb8aa3b, v22
	v_exp_f32_e32 v54, v54
	v_sub_f32_e32 v53, 1.0, v50
	v_add_f32_e32 v54, 1.0, v54
	v_div_scale_f32 v55, s[18:19], v54, v54, 1.0
	v_rcp_f32_e32 v56, v55
	s_nop 0
	v_fma_f32 v57, -v55, v56, 1.0
	v_fmac_f32_e32 v56, v57, v56
	v_div_scale_f32 v57, vcc, 1.0, v54, 1.0
	v_mul_f32_e32 v58, v57, v56
	v_fma_f32 v59, -v55, v58, v57
	v_fmac_f32_e32 v58, v59, v56
	v_fma_f32 v55, -v55, v58, v57
	v_div_fmas_f32 v55, v55, v56, v58
	v_div_fixup_f32 v54, v55, v54, 1.0
	v_fmac_f32_e32 v50, v54, v53
	v_mul_f32_e32 v54, 0xbfb8aa3b, v23
	v_exp_f32_e32 v54, v54
	v_sub_f32_e32 v53, 1.0, v51
	v_add_f32_e32 v54, 1.0, v54
	v_div_scale_f32 v55, s[18:19], v54, v54, 1.0
	v_rcp_f32_e32 v56, v55
	s_nop 0
	v_fma_f32 v57, -v55, v56, 1.0
	v_fmac_f32_e32 v56, v57, v56
	v_div_scale_f32 v57, vcc, 1.0, v54, 1.0
	v_mul_f32_e32 v58, v57, v56
	v_fma_f32 v59, -v55, v58, v57
	v_fmac_f32_e32 v58, v59, v56
	v_fma_f32 v55, -v55, v58, v57
	v_div_fmas_f32 v55, v55, v56, v58
	v_div_fixup_f32 v54, v55, v54, 1.0
	v_fmac_f32_e32 v51, v54, v53
	ds_write_b128 v125, v[48:51] offset:16384
	s_waitcnt vmcnt(9)
	ds_write_b128 v125, v[40:43] offset:49152
	v_mul_f32_e32 v48, 0xbfb8aa3b, v32
	v_mul_f32_e32 v49, 0xbfb8aa3b, v33
	v_exp_f32_e32 v48, v48
	v_exp_f32_e32 v49, v49
	v_mul_f32_e32 v50, 0xbfb8aa3b, v34
	v_mul_f32_e32 v51, 0xbfb8aa3b, v35
	v_exp_f32_e32 v50, v50
	v_add_f32_e64 v48, v48, 1.0
	v_add_f32_e64 v49, v49, 1.0
	v_exp_f32_e32 v51, v51
	v_div_scale_f32 v53, s[18:19], v49, v49, 1.0
	v_rcp_f32_e32 v54, v53
	v_add_f32_e64 v50, v50, 1.0
	v_add_f32_e64 v51, v51, 1.0
	v_fma_f32 v55, -v53, v54, 1.0
	v_fmac_f32_e32 v54, v55, v54
	v_div_scale_f32 v55, vcc, 1.0, v49, 1.0
	v_mul_f32_e32 v56, v55, v54
	v_fma_f32 v57, -v53, v56, v55
	v_fmac_f32_e32 v56, v57, v54
	v_fma_f32 v53, -v53, v56, v55
	v_div_fmas_f32 v53, v53, v54, v56
	v_div_fixup_f32 v49, v53, v49, 1.0
	v_div_scale_f32 v53, s[18:19], v48, v48, 1.0
	v_rcp_f32_e32 v54, v53
	s_nop 0
	v_fma_f32 v55, -v53, v54, 1.0
	v_fmac_f32_e32 v54, v55, v54
	v_div_scale_f32 v55, vcc, 1.0, v48, 1.0
	v_mul_f32_e32 v56, v55, v54
	v_fma_f32 v57, -v53, v56, v55
	v_fmac_f32_e32 v56, v57, v54
	v_fma_f32 v53, -v53, v56, v55
	v_div_fmas_f32 v53, v53, v54, v56
	v_div_fixup_f32 v48, v53, v48, 1.0
	v_div_scale_f32 v53, s[18:19], v51, v51, 1.0
	v_rcp_f32_e32 v54, v53
	v_mul_f32_e64 v48, v32, v48
	v_mul_f32_e64 v49, v33, v49
	v_fma_f32 v55, -v53, v54, 1.0
	v_fmac_f32_e32 v54, v55, v54
	v_div_scale_f32 v55, vcc, 1.0, v51, 1.0
	v_mul_f32_e32 v56, v55, v54
	v_fma_f32 v57, -v53, v56, v55
	v_fmac_f32_e32 v56, v57, v54
	v_fma_f32 v53, -v53, v56, v55
	v_div_fmas_f32 v53, v53, v54, v56
	v_div_fixup_f32 v51, v53, v51, 1.0
	v_div_scale_f32 v53, s[18:19], v50, v50, 1.0
	v_rcp_f32_e32 v54, v53
	s_nop 0
	v_fma_f32 v55, -v53, v54, 1.0
	v_fmac_f32_e32 v54, v55, v54
	v_div_scale_f32 v55, vcc, 1.0, v50, 1.0
	v_mul_f32_e32 v56, v55, v54
	v_fma_f32 v57, -v53, v56, v55
	v_fmac_f32_e32 v56, v57, v54
	v_fma_f32 v53, -v53, v56, v55
	v_div_fmas_f32 v53, v53, v54, v56
	v_div_fixup_f32 v50, v53, v50, 1.0
	v_mul_f32_e64 v50, v34, v50
	v_mul_f32_e64 v51, v35, v51
	ds_write_b128 v128, v[48:51]
	v_mov_b32_e32 v49, 0
	s_and_b64 vcc, exec, s[10:11]
	v_mov_b32_e32 v48, 0
	s_cbranch_vccz .LBB0_469
	s_and_b64 vcc, exec, s[10:11]
	s_cbranch_vccz .LBB0_470

.LBB0_448:
	v_mul_f32_e32 v53, 0xbfb8aa3b, v28
	v_exp_f32_e32 v53, v53
	v_sub_f32_e32 v52, 1.0, v48
	s_add_i32 s18, s7, s34
	s_cmpk_gt_i32 s18, 0x1ff
	v_add_f32_e32 v53, 1.0, v53
	v_div_scale_f32 v54, s[10:11], v53, v53, 1.0
	v_rcp_f32_e32 v55, v54
	s_cselect_b64 s[20:21], -1, 0
	s_waitcnt vmcnt(0)
	v_mov_b32_e32 v140, v81
	v_mov_b32_e32 v139, v80
	v_fma_f32 v56, -v54, v55, 1.0
	v_fmac_f32_e32 v55, v56, v55
	v_div_scale_f32 v56, vcc, 1.0, v53, 1.0
	v_mul_f32_e32 v57, v56, v55
	v_fma_f32 v58, -v54, v57, v56
	v_fmac_f32_e32 v57, v58, v55
	v_fma_f32 v54, -v54, v57, v56
	v_div_fmas_f32 v54, v54, v55, v57
	v_div_fixup_f32 v53, v54, v53, 1.0
	v_fmac_f32_e32 v48, v53, v52
	v_mul_f32_e32 v53, 0xbfb8aa3b, v29
	v_exp_f32_e32 v53, v53
	v_sub_f32_e32 v52, 1.0, v49
	v_mov_b32_e32 v138, v83
	v_mov_b32_e32 v137, v82
	v_add_f32_e32 v53, 1.0, v53
	v_div_scale_f32 v54, s[10:11], v53, v53, 1.0
	v_rcp_f32_e32 v55, v54
	v_mov_b32_e32 v136, v85
	v_mov_b32_e32 v135, v84
	v_mov_b32_e32 v134, v87
	v_fma_f32 v56, -v54, v55, 1.0
	v_fmac_f32_e32 v55, v56, v55
	v_div_scale_f32 v56, vcc, 1.0, v53, 1.0
	v_mul_f32_e32 v57, v56, v55
	v_fma_f32 v58, -v54, v57, v56
	v_fmac_f32_e32 v57, v58, v55
	v_fma_f32 v54, -v54, v57, v56
	v_div_fmas_f32 v54, v54, v55, v57
	v_div_fixup_f32 v53, v54, v53, 1.0
	v_fmac_f32_e32 v49, v53, v52
	v_mul_f32_e32 v53, 0xbfb8aa3b, v30
	v_exp_f32_e32 v53, v53
	v_sub_f32_e32 v52, 1.0, v50
	v_mov_b32_e32 v133, v86
	v_add_f32_e32 v53, 1.0, v53
	v_div_scale_f32 v54, s[10:11], v53, v53, 1.0
	v_rcp_f32_e32 v55, v54
	s_nop 0
	v_fma_f32 v56, -v54, v55, 1.0
	v_fmac_f32_e32 v55, v56, v55
	v_div_scale_f32 v56, vcc, 1.0, v53, 1.0
	v_mul_f32_e32 v57, v56, v55
	v_fma_f32 v58, -v54, v57, v56
	v_fmac_f32_e32 v57, v58, v55
	v_fma_f32 v54, -v54, v57, v56
	v_div_fmas_f32 v54, v54, v55, v57
	v_div_fixup_f32 v53, v54, v53, 1.0
	v_fmac_f32_e32 v50, v53, v52
	v_mul_f32_e32 v53, 0xbfb8aa3b, v31
	v_exp_f32_e32 v53, v53
	v_sub_f32_e32 v52, 1.0, v51
	v_add_f32_e32 v53, 1.0, v53
	v_div_scale_f32 v54, s[10:11], v53, v53, 1.0
	v_rcp_f32_e32 v55, v54
	s_nop 0
	v_fma_f32 v56, -v54, v55, 1.0
	v_fmac_f32_e32 v55, v56, v55
	v_div_scale_f32 v56, vcc, 1.0, v53, 1.0
	v_mul_f32_e32 v57, v56, v55
	v_fma_f32 v58, -v54, v57, v56
	v_fmac_f32_e32 v57, v58, v55
	v_fma_f32 v54, -v54, v57, v56
	v_div_fmas_f32 v54, v54, v55, v57
	v_div_fixup_f32 v53, v54, v53, 1.0
	v_fmac_f32_e32 v51, v53, v52
	ds_write_b128 v125, v[48:51] offset:24576
	ds_write_b128 v125, v[36:39] offset:57344
	v_mul_f32_e32 v48, 0xbfb8aa3b, v44
	v_mul_f32_e32 v49, 0xbfb8aa3b, v45
	v_exp_f32_e32 v48, v48
	v_exp_f32_e32 v49, v49
	v_mul_f32_e32 v50, 0xbfb8aa3b, v46
	v_mul_f32_e32 v51, 0xbfb8aa3b, v47
	v_exp_f32_e32 v50, v50
	v_add_f32_e64 v48, v48, 1.0
	v_add_f32_e64 v49, v49, 1.0
	v_exp_f32_e32 v51, v51
	v_div_scale_f32 v52, s[10:11], v49, v49, 1.0
	v_rcp_f32_e32 v53, v52
	v_add_f32_e64 v50, v50, 1.0
	v_add_f32_e64 v51, v51, 1.0
	v_fma_f32 v54, -v52, v53, 1.0
	v_fmac_f32_e32 v53, v54, v53
	v_div_scale_f32 v54, vcc, 1.0, v49, 1.0
	v_mul_f32_e32 v55, v54, v53
	v_fma_f32 v56, -v52, v55, v54
	v_fmac_f32_e32 v55, v56, v53
	v_fma_f32 v52, -v52, v55, v54
	v_div_fmas_f32 v52, v52, v53, v55
	v_div_fixup_f32 v49, v52, v49, 1.0
	v_div_scale_f32 v52, s[10:11], v48, v48, 1.0
	v_rcp_f32_e32 v53, v52
	s_nop 0
	v_fma_f32 v54, -v52, v53, 1.0
	v_fmac_f32_e32 v53, v54, v53
	v_div_scale_f32 v54, vcc, 1.0, v48, 1.0
	v_mul_f32_e32 v55, v54, v53
	v_fma_f32 v56, -v52, v55, v54
	v_fmac_f32_e32 v55, v56, v53
	v_fma_f32 v52, -v52, v55, v54
	v_div_fmas_f32 v52, v52, v53, v55
	v_div_fixup_f32 v48, v52, v48, 1.0
	v_div_scale_f32 v52, s[10:11], v51, v51, 1.0
	v_rcp_f32_e32 v53, v52
	v_mul_f32_e64 v48, v44, v48
	v_mul_f32_e64 v49, v45, v49
	v_fma_f32 v54, -v52, v53, 1.0
	v_fmac_f32_e32 v53, v54, v53
	v_div_scale_f32 v54, vcc, 1.0, v51, 1.0
	v_mul_f32_e32 v55, v54, v53
	v_fma_f32 v56, -v52, v55, v54
	v_fmac_f32_e32 v55, v56, v53
	v_fma_f32 v52, -v52, v55, v54
	v_div_fmas_f32 v52, v52, v53, v55
	v_div_fixup_f32 v51, v52, v51, 1.0
	v_div_scale_f32 v52, s[10:11], v50, v50, 1.0
	v_rcp_f32_e32 v53, v52
	s_nop 0
	v_fma_f32 v54, -v52, v53, 1.0
	v_fmac_f32_e32 v53, v54, v53
	v_div_scale_f32 v54, vcc, 1.0, v50, 1.0
	v_mul_f32_e32 v55, v54, v53
	v_fma_f32 v56, -v52, v55, v54
	v_fmac_f32_e32 v55, v56, v53
	v_fma_f32 v52, -v52, v55, v54
	v_div_fmas_f32 v52, v52, v53, v55
	v_div_fixup_f32 v50, v52, v50, 1.0
	v_mul_f32_e64 v50, v46, v50
	v_mul_f32_e64 v51, v47, v51
	s_and_b64 vcc, exec, s[20:21]
	ds_write_b128 v129, v[48:51]
	s_waitcnt lgkmcnt(0)
	s_barrier
	s_cbranch_vccnz .LBB0_450
	s_lshl_b32 s1, s18, 5
	s_lshl_b32 s10, s18, 8
	s_and_b32 s1, s1, 0xffffff80
	s_and_b32 s40, s10, 0x300
	v_lshl_add_u64 v[28:29], v[102:103], 0, s[40:41]
	v_add_u32_e32 v0, s1, v99
	v_add_u32_e32 v4, s1, v118
	v_mad_i64_i32 v[16:17], s[10:11], v0, s75, v[28:29]
	v_mad_i64_i32 v[20:21], s[10:11], v4, s75, v[28:29]
	global_load_dwordx4 v[0:3], v[16:17], off offset:1024
	global_load_dwordx4 v[8:11], v[16:17], off
	global_load_dwordx4 v[4:7], v[20:21], off offset:1024
	global_load_dwordx4 v[12:15], v[20:21], off offset:2048
	s_nop 0
	global_load_dwordx4 v[16:19], v[16:17], off offset:2048
	s_nop 0
	global_load_dwordx4 v[24:27], v[20:21], off
	v_add_u32_e32 v20, s1, v119
	v_add_u32_e32 v30, s1, v120
	v_mad_i64_i32 v[40:41], s[10:11], v20, s75, v[28:29]
	v_mad_i64_i32 v[44:45], s[10:11], v30, s75, v[28:29]
	s_ashr_i32 s19, s18, 31
	s_lshl_b64 s[10:11], s[18:19], 14
	v_lshl_add_u64 v[48:49], v[96:97], 0, s[10:11]
	global_load_dwordx4 v[20:23], v[40:41], off offset:1024
	global_load_dwordx4 v[32:35], v[40:41], off
	global_load_dwordx4 v[28:31], v[44:45], off offset:1024
	global_load_dwordx4 v[36:39], v[44:45], off offset:2048
	s_nop 0
	global_load_dwordx4 v[40:43], v[40:41], off offset:2048
	s_nop 0
	global_load_dwordx4 v[44:47], v[44:45], off
	s_nop 0
	global_load_dword v133, v[48:49], off
	global_load_dword v134, v[48:49], off offset:256
	global_load_dword v135, v[48:49], off offset:512
	global_load_dword v136, v[48:49], off offset:768
	global_load_dword v137, v[48:49], off offset:1024
	global_load_dword v138, v[48:49], off offset:1280
	global_load_dword v139, v[48:49], off offset:1536
	global_load_dword v140, v[48:49], off offset:1792

.LBB0_452:
	s_waitcnt lgkmcnt(2)
	v_add_f32_e64 v86, v86, -v88
	v_add_f32_e64 v87, v87, -v88
	v_add_u32_e32 v91, s1, v121
	v_fma_f32 v86, v60, v86, v88
	v_fma_f32 v87, v61, v87, v88
	v_add_f32_e64 v60, v82, -v88
	v_add_f32_e64 v61, v83, -v88
	s_waitcnt lgkmcnt(1)
	v_fma_f32 v52, v52, v86, 0
	v_fma_f32 v92, v56, v60, v88
	v_fma_f32 v93, v57, v61, v88
	v_add_f32_e64 v56, v84, -v88
	v_add_f32_e64 v57, v85, -v88
	s_waitcnt lgkmcnt(0)
	v_fmac_f32_e32 v52, v48, v92
	v_fmac_f32_e32 v52, v53, v87
	v_fma_f32 v84, v62, v56, v88
	v_fma_f32 v85, v63, v57, v88
	v_add_f32_e64 v56, v80, -v88
	v_add_f32_e64 v57, v81, -v88
	v_fmac_f32_e32 v52, v49, v93
	v_fma_f32 v80, v58, v56, v88
	v_fma_f32 v81, v59, v57, v88
	v_fmac_f32_e32 v52, v54, v84
	v_add_u32_e32 v104, s1, v131
	v_add_u32_e32 v64, 0x10100, v91
	v_add_u32_e32 v68, 0x10110, v91
	v_fmac_f32_e32 v52, v50, v80
	ds_read_b128 v[76:79], v91 offset:256
	ds_read_b128 v[72:75], v91 offset:272
	ds_read_b32 v90, v104 offset:256
	ds_read_b128 v[64:67], v64
	ds_read_b128 v[68:71], v68
	v_fmac_f32_e32 v52, v55, v85
	v_fmac_f32_e32 v52, v51, v81
	s_nop 1
	v_add_f32_dpp v48, v52, v52 quad_perm:[1,0,3,2] row_mask:0xf bank_mask:0xf bound_ctrl:1
	s_nop 1
	v_add_f32_dpp v48, v48, v48 quad_perm:[2,3,0,1] row_mask:0xf bank_mask:0xf bound_ctrl:1
	s_nop 1
	v_mov_b32_dpp v49, v48 row_half_mirror row_mask:0xf bank_mask:0xf bound_ctrl:1
	s_and_saveexec_b64 s[10:11], s[8:9]
	v_add_f32_e32 v48, v48, v49
	ds_write_b32 v104, v48
	s_or_b64 exec, exec, s[10:11]
	s_waitcnt lgkmcnt(2)
	v_add_f32_e64 v86, v86, -v90
	v_add_f32_e64 v87, v87, -v90
	v_add_u32_e32 v48, 0x10200, v91
	v_fma_f32 v86, v76, v86, v90
	v_fma_f32 v87, v77, v87, v90
	v_add_f32_e64 v76, v92, -v90
	v_add_f32_e64 v77, v93, -v90
	s_waitcnt lgkmcnt(1)
	v_fma_f32 v64, v64, v86, 0
	v_fma_f32 v88, v72, v76, v90
	v_fma_f32 v89, v73, v77, v90
	v_add_f32_e64 v72, v84, -v90
	v_add_f32_e64 v73, v85, -v90
	s_waitcnt lgkmcnt(0)
	v_fmac_f32_e32 v64, v68, v88
	v_fmac_f32_e32 v64, v65, v87
	v_fma_f32 v92, v78, v72, v90
	v_fma_f32 v93, v79, v73, v90
	v_add_f32_e64 v72, v80, -v90
	v_add_f32_e64 v73, v81, -v90
	v_fmac_f32_e32 v64, v69, v89
	v_fma_f32 v94, v74, v72, v90
	v_fma_f32 v95, v75, v73, v90
	v_fmac_f32_e32 v64, v66, v92
	v_add_u32_e32 v52, 0x10210, v91
	v_fmac_f32_e32 v64, v70, v94
	ds_read_b128 v[60:63], v91 offset:512
	ds_read_b128 v[56:59], v91 offset:528
	ds_read_b32 v82, v104 offset:512
	ds_read_b128 v[48:51], v48
	ds_read_b128 v[52:55], v52
	v_fmac_f32_e32 v64, v67, v93
	v_fmac_f32_e32 v64, v71, v95
	s_nop 1
	v_add_f32_dpp v64, v64, v64 quad_perm:[1,0,3,2] row_mask:0xf bank_mask:0xf bound_ctrl:1
	s_nop 1
	v_add_f32_dpp v64, v64, v64 quad_perm:[2,3,0,1] row_mask:0xf bank_mask:0xf bound_ctrl:1
	s_nop 1
	v_mov_b32_dpp v65, v64 row_half_mirror row_mask:0xf bank_mask:0xf bound_ctrl:1
	s_and_saveexec_b64 s[10:11], s[8:9]
	v_add_f32_e32 v64, v64, v65
	ds_write_b32 v104, v64 offset:256
	s_or_b64 exec, exec, s[10:11]
	s_waitcnt lgkmcnt(2)
	v_add_f32_e64 v84, v86, -v82
	v_add_f32_e64 v85, v87, -v82
	ds_read_b128 v[76:79], v91 offset:768
	ds_read_b128 v[72:75], v91 offset:784
	v_fma_f32 v84, v60, v84, v82
	v_fma_f32 v85, v61, v85, v82
	v_add_f32_e64 v60, v88, -v82
	v_add_f32_e64 v61, v89, -v82
	v_add_u32_e32 v64, 0x10300, v91
	v_add_u32_e32 v68, 0x10310, v91
	v_fma_f32 v90, v56, v60, v82
	v_fma_f32 v91, v57, v61, v82
	s_waitcnt lgkmcnt(3)
	v_fma_f32 v48, v48, v84, 0
	s_waitcnt lgkmcnt(2)
	v_fmac_f32_e32 v48, v52, v90
	v_add_f32_e64 v56, v92, -v82
	v_add_f32_e64 v57, v93, -v82
	v_fmac_f32_e32 v48, v49, v85
	v_fma_f32 v92, v62, v56, v82
	v_fma_f32 v93, v63, v57, v82
	v_add_f32_e64 v56, v94, -v82
	v_add_f32_e64 v57, v95, -v82
	v_fmac_f32_e32 v48, v53, v91
	v_fma_f32 v94, v58, v56, v82
	v_fma_f32 v95, v59, v57, v82
	v_fmac_f32_e32 v48, v50, v92
	v_fmac_f32_e32 v48, v54, v94
	ds_read_b32 v80, v104 offset:768
	ds_read_b128 v[64:67], v64
	ds_read_b128 v[68:71], v68
	v_fmac_f32_e32 v48, v51, v93
	v_fmac_f32_e32 v48, v55, v95
	s_nop 1
	v_add_f32_dpp v48, v48, v48 quad_perm:[1,0,3,2] row_mask:0xf bank_mask:0xf bound_ctrl:1
	s_nop 1
	v_add_f32_dpp v48, v48, v48 quad_perm:[2,3,0,1] row_mask:0xf bank_mask:0xf bound_ctrl:1
	s_nop 1
	v_mov_b32_dpp v49, v48 row_half_mirror row_mask:0xf bank_mask:0xf bound_ctrl:1
	s_and_saveexec_b64 s[10:11], s[8:9]
	v_add_f32_e32 v48, v48, v49
	ds_write_b32 v104, v48 offset:512
	s_or_b64 exec, exec, s[10:11]
	s_waitcnt lgkmcnt(2)
	v_add_f32_e64 v82, v84, -v80
	v_add_f32_e64 v83, v85, -v80
	s_cmpk_lg_i32 s1, 0x7c00
	v_fma_f32 v86, v76, v82, v80
	v_fma_f32 v87, v77, v83, v80
	v_add_f32_e64 v76, v90, -v80
	v_add_f32_e64 v77, v91, -v80
	s_waitcnt lgkmcnt(1)
	v_fma_f32 v64, v64, v86, 0
	v_fma_f32 v82, v72, v76, v80
	v_fma_f32 v83, v73, v77, v80
	s_cselect_b32 s10, s19, 0x1fc0
	s_waitcnt lgkmcnt(0)
	v_fmac_f32_e32 v64, v68, v82
	s_lshl_b32 s10, s10, 2
	v_add_f32_e64 v72, v92, -v80
	v_add_f32_e64 v73, v93, -v80
	v_fmac_f32_e32 v64, v65, v87
	v_add_u32_e32 v48, s10, v121
	v_fma_f32 v84, v78, v72, v80
	v_fma_f32 v85, v79, v73, v80
	v_add_f32_e64 v72, v94, -v80
	v_add_f32_e64 v73, v95, -v80
	v_fmac_f32_e32 v64, v69, v83
	ds_read_b128 v[60:63], v48
	ds_read_b128 v[56:59], v48 offset:16
	v_add_u32_e32 v48, s10, v122
	v_add_u32_e32 v49, s10, v123
	v_fma_f32 v81, v75, v73, v80
	v_fma_f32 v80, v74, v72, v80
	v_fmac_f32_e32 v64, v66, v84
	ds_read_b32 v88, v48 offset:32768
	ds_read_b128 v[52:55], v49
	ds_read_b128 v[48:51], v49 offset:16
	v_fmac_f32_e32 v64, v70, v80
	v_fmac_f32_e32 v64, v67, v85
	v_fmac_f32_e32 v64, v71, v81
	s_nop 1
	v_add_f32_dpp v64, v64, v64 quad_perm:[1,0,3,2] row_mask:0xf bank_mask:0xf bound_ctrl:1
	s_nop 1
	v_add_f32_dpp v64, v64, v64 quad_perm:[2,3,0,1] row_mask:0xf bank_mask:0xf bound_ctrl:1
	s_nop 1
	v_mov_b32_dpp v65, v64 row_half_mirror row_mask:0xf bank_mask:0xf bound_ctrl:1
	s_and_saveexec_b64 s[10:11], s[8:9]
	s_cbranch_execz .LBB0_451
	v_add_f32_e32 v64, v64, v65
	ds_write_b32 v104, v64 offset:768
	s_branch .LBB0_451
